# speedup vs baseline: 1.0461x; 1.0040x over previous
; __device__ __forceinline__ unsigned pk2(float lo, float hi) { f32x2 v = {lo, hi}; bf16x2_t b = __builtin_convertvector(v, bf16x2_t); return __builtin_bit_cast(unsigned, b); }
; __device__ __forceinline__ void row_phase(const Params& p, const int li_post, const int li_pre, const int gw, const int ngw, const int lane) {
;     ...
;     for (int i = i0; i < SEQ; i += istep) {
;         const int row = b * SEQ + i;
;         f32x4 v[8];
; #pragma unroll
;         for (int j = 0; j < 8; ++j) {
;             if (li_post <= 0) v[j] = *(const f32x4*)(p.x + (size_t)row * DM + j * 256 + lane * 4);
;             else { const u32x2 xx = *(const u32x2*)((const bf16_t*)(p.out + (size_t)row * DM) + j * 256 + lane * 4); v[j] = (f32x4){bflo(xx.x), bfhi(xx.x), bflo(xx.y), bfhi(xx.y)}; }
;         }
;         if (li_post >= 0) {
;             f32x4 y[8]; float ss = 0.f;
; #pragma unroll
;             for (int j = 0; j < 8; ++j) { const u32x2 yy = *(const u32x2*)(Y + (size_t)row * DM + j * 256 + lane * 4); y[j] = (f32x4){bflo(yy.x), bfhi(yy.x), bflo(yy.y), bfhi(yy.y)}; ss += (y[j][0] * y[j][0] + y[j][1] * y[j][1]) + (y[j][2] * y[j][2] + y[j][3] * y[j][3]); }
;             ss = wave_sum(ss);
;             const float r = 1.0f / sqrtf(ss * (1.0f / DM) + EPS);
; #pragma unroll
;             for (int j = 0; j < 8; ++j) { const int col = j * 256 + lane * 4;
;                 v[j] = v[j] + (y[j] * r) * GP[j];
;                 if (li_post == 3) *(f32x4*)(p.out + (size_t)row * DM + col) = v[j];
;                 else { u32x2 w; w.x = pk2(v[j][0], v[j][1]); w.y = pk2(v[j][2], v[j][3]); *(u32x2*)((bf16_t*)(p.out + (size_t)row * DM) + col) = w; } }
;         }
;         if (li_pre >= 0) {
;             float ss = 0.f;
; #pragma unroll
;             for (int j = 0; j < 8; ++j) ss += (v[j][0] * v[j][0] + v[j][1] * v[j][1]) + (v[j][2] * v[j][2] + v[j][3] * v[j][3]);
;             ss = wave_sum(ss);
.LBB0_149:
	global_load_dwordx4 v[52:55], v[98:99], off offset:-4096
	global_load_dwordx4 v[48:51], v[98:99], off offset:-3072
	global_load_dwordx4 v[44:47], v[98:99], off offset:-2048
	global_load_dwordx4 v[32:35], v[98:99], off offset:1024
	global_load_dwordx4 v[56:59], v[98:99], off offset:-1024
	global_load_dwordx4 v[36:39], v[98:99], off offset:2048
	global_load_dwordx4 v[60:63], v[98:99], off
	global_load_dwordx4 v[40:43], v[98:99], off offset:3072
	s_add_i32 s26, s26, s0
	v_lshl_add_u64 v[98:99], v[98:99], 0, s[16:17]
	s_cmpk_lt_i32 s26, 0x2000
	s_waitcnt vmcnt(7)
	v_mov_b32_e32 v110, v53
	s_waitcnt vmcnt(6)
	v_mov_b32_e32 v111, v49
	s_waitcnt vmcnt(5)
	v_pk_mul_f32 v[114:115], v[46:47], v[46:47]
	v_pk_mul_f32 v[116:117], v[44:45], v[44:45]
	s_waitcnt vmcnt(4)
	v_pk_mul_f32 v[118:119], v[34:35], v[34:35]
	v_pk_mul_f32 v[120:121], v[32:33], v[32:33]
	v_mov_b32_e32 v122, v55
	v_mov_b32_e32 v123, v51
	v_mov_b32_e32 v108, v52
	v_mov_b32_e32 v109, v48
	v_mov_b32_e32 v112, v54
	v_mov_b32_e32 v113, v50
	v_pk_mov_b32 v[132:133], v[116:117], v[114:115] op_sel:[1,0]
	v_mov_b32_e32 v117, v115
	v_pk_mov_b32 v[114:115], v[120:121], v[118:119] op_sel:[1,0]
	v_mov_b32_e32 v121, v119
	v_pk_mul_f32 v[110:111], v[110:111], v[110:111]
	v_pk_mul_f32 v[118:119], v[122:123], v[122:123]
	v_pk_fma_f32 v[108:109], v[108:109], v[108:109], v[110:111]
	v_pk_fma_f32 v[110:111], v[112:113], v[112:113], v[118:119]
	s_waitcnt vmcnt(3)
	v_mul_f32_e32 v124, v56, v56
	v_mul_f32_e32 v126, v58, v58
	v_pk_add_f32 v[112:113], v[132:133], v[116:117]
	v_pk_add_f32 v[108:109], v[108:109], v[110:111]
	v_pk_fma_f32 v[122:123], v[56:57], v[56:57], v[124:125] op_sel_hi:[1,1,0]
	v_pk_fma_f32 v[124:125], v[58:59], v[58:59], v[126:127] op_sel_hi:[1,1,0]
	v_pk_add_f32 v[110:111], v[112:113], v[112:113] op_sel_hi:[0,1]
	v_pk_add_f32 v[108:109], v[108:109], v[108:109] op_sel_hi:[0,1]
	s_waitcnt vmcnt(1)
	v_mul_f32_e32 v122, v60, v60
	v_mul_f32_e32 v124, v61, v61
	v_mul_f32_e32 v110, v62, v62
	v_mul_f32_e32 v108, v63, v63
	v_pk_add_f32 v[112:113], v[122:123], v[124:125]
	v_pk_add_f32 v[108:109], v[110:111], v[108:109]
	v_mul_f32_e32 v128, v36, v36
	v_mul_f32_e32 v130, v38, v38
	v_pk_add_f32 v[114:115], v[114:115], v[120:121]
	v_pk_add_f32 v[108:109], v[112:113], v[108:109]
	v_pk_fma_f32 v[126:127], v[36:37], v[36:37], v[128:129] op_sel_hi:[1,1,0]
	v_pk_fma_f32 v[128:129], v[38:39], v[38:39], v[130:131] op_sel_hi:[1,1,0]
	v_pk_add_f32 v[114:115], v[114:115], v[114:115] op_sel_hi:[0,1]
	v_pk_add_f32 v[108:109], v[108:109], v[108:109] op_sel_hi:[0,1]
	s_waitcnt vmcnt(0)
; __device__ __forceinline__ unsigned pk2(float lo, float hi) { f32x2 v = {lo, hi}; bf16x2_t b = __builtin_convertvector(v, bf16x2_t); return __builtin_bit_cast(unsigned, b); }
; __device__ __forceinline__ float wave_sum(float v) {
; #pragma unroll
;     for (int o = 1; o < 64; o <<= 1) v += __shfl_xor(v, o);
;     return v;
; __device__ __forceinline__ void row_phase(const Params& p, const int li_post, const int li_pre, const int gw, const int ngw, const int lane) {
;     ...
;         if (li_pre >= 0) {
;             float ss = 0.f;
; #pragma unroll
;             for (int j = 0; j < 8; ++j) ss += (v[j][0] * v[j][0] + v[j][1] * v[j][1]) + (v[j][2] * v[j][2] + v[j][3] * v[j][3]);
;             ss = wave_sum(ss);
;             const float r = 1.0f / sqrtf(ss * (1.0f / DM) + EPS);
; #pragma unroll
;             for (int j = 0; j < 8; ++j) { const int col = j * 256 + lane * 4;
;                 const f32x4 h = (v[j] * r) * PA[j] + SH[j];
;                 u32x2 w; w.x = pk2(h[0], h[1]); w.y = pk2(h[2], h[3]);
;                 *(u32x2*)(H + (size_t)row * DM + col) = w; }
	v_mul_f32_e32 v126, v40, v40
	v_mul_f32_e32 v128, v41, v41
	v_mul_f32_e32 v114, v42, v42
	v_mul_f32_e32 v108, v43, v43
	v_pk_add_f32 v[116:117], v[126:127], v[128:129]
	v_pk_add_f32 v[108:109], v[114:115], v[108:109]
	s_nop 0
	v_pk_add_f32 v[108:109], v[116:117], v[108:109]
	s_nop 0
	v_add_f32_e32 v108, v108, v109
	s_nop 1
	v_add_f32_dpp v109, v108, v108 quad_perm:[1,0,3,2] row_mask:0xf bank_mask:0xf
	s_nop 1
	v_add_f32_dpp v108, v109, v109 quad_perm:[2,3,0,1] row_mask:0xf bank_mask:0xf
	s_nop 1
	v_add_f32_dpp v109, v108, v108 row_half_mirror row_mask:0xf bank_mask:0xf
	s_nop 1
	v_add_f32_dpp v108, v109, v109 row_mirror row_mask:0xf bank_mask:0xf
	v_mov_b32_e32 v109, v108
	s_nop 1
	v_permlane16_swap_b32_e32 v108, v109
	s_nop 1
	v_add_f32_e32 v108, v108, v109
	v_mov_b32_e32 v109, v108
	s_nop 1
	v_permlane32_swap_b32_e32 v108, v109
	s_nop 1
	v_add_f32_e32 v108, v108, v109
	v_fmamk_f32 v108, v108, 0x3a000000, v106
	v_mul_f32_e32 v109, 0x4f800000, v108
	v_cmp_gt_f32_e32 vcc, s1, v108
	s_nop 1
	v_cndmask_b32_e32 v108, v108, v109, vcc
	v_sqrt_f32_e32 v109, v108
	s_nop 0
	v_add_u32_e32 v110, -1, v109
	v_add_u32_e32 v111, 1, v109
	v_fma_f32 v112, -v110, v109, v108
	v_fma_f32 v113, -v111, v109, v108
	v_cmp_ge_f32_e64 s[2:3], 0, v112
	s_nop 1
	v_cndmask_b32_e64 v109, v109, v110, s[2:3]
	v_cmp_lt_f32_e64 s[2:3], 0, v113
	s_nop 1
	v_cndmask_b32_e64 v109, v109, v111, s[2:3]
	v_mul_f32_e32 v110, 0x37800000, v109
	v_cndmask_b32_e32 v109, v109, v110, vcc
	v_cmp_class_f32_e32 vcc, v108, v107
	s_nop 1
	v_cndmask_b32_e32 v108, v109, v108, vcc
	v_div_scale_f32 v109, s[2:3], v108, v108, 1.0
	v_rcp_f32_e32 v111, v109
	v_div_scale_f32 v110, vcc, 1.0, v108, 1.0
	v_fma_f32 v112, -v109, v111, 1.0
	v_fmac_f32_e32 v111, v112, v111
	v_mul_f32_e32 v112, v110, v111
	v_fma_f32 v113, -v109, v112, v110
	v_fmac_f32_e32 v112, v113, v111
	v_fma_f32 v109, -v109, v112, v110
	v_div_fmas_f32 v109, v109, v111, v112
	v_div_fixup_f32 v108, v109, v108, 1.0
	v_pk_mul_f32 v[52:53], v[52:53], v[108:109] op_sel_hi:[1,0]
	v_pk_mul_f32 v[54:55], v[54:55], v[108:109] op_sel_hi:[1,0]
	v_pk_mul_f32 v[48:49], v[48:49], v[108:109] op_sel_hi:[1,0]
	v_pk_mul_f32 v[50:51], v[50:51], v[108:109] op_sel_hi:[1,0]
	v_pk_mul_f32 v[44:45], v[44:45], v[108:109] op_sel_hi:[1,0]
	v_pk_mul_f32 v[46:47], v[46:47], v[108:109] op_sel_hi:[1,0]
	v_pk_mul_f32 v[56:57], v[56:57], v[108:109] op_sel_hi:[1,0]
	v_pk_mul_f32 v[58:59], v[58:59], v[108:109] op_sel_hi:[1,0]
	v_pk_mul_f32 v[60:61], v[60:61], v[108:109] op_sel_hi:[1,0]
	v_pk_mul_f32 v[62:63], v[62:63], v[108:109] op_sel_hi:[1,0]
	v_pk_mul_f32 v[32:33], v[32:33], v[108:109] op_sel_hi:[1,0]
	v_pk_mul_f32 v[34:35], v[34:35], v[108:109] op_sel_hi:[1,0]
	v_pk_mul_f32 v[36:37], v[36:37], v[108:109] op_sel_hi:[1,0]
	v_pk_mul_f32 v[38:39], v[38:39], v[108:109] op_sel_hi:[1,0]
	v_pk_mul_f32 v[40:41], v[40:41], v[108:109] op_sel_hi:[1,0]
	v_pk_mul_f32 v[42:43], v[42:43], v[108:109] op_sel_hi:[1,0]
	v_pk_fma_f32 v[54:55], v[64:65], v[54:55], v[2:3]
	v_pk_fma_f32 v[52:53], v[66:67], v[52:53], v[0:1]
	v_pk_fma_f32 v[50:51], v[68:69], v[50:51], v[6:7]
	v_pk_fma_f32 v[48:49], v[70:71], v[48:49], v[4:5]
	v_pk_fma_f32 v[46:47], v[72:73], v[46:47], v[10:11]
	v_pk_fma_f32 v[44:45], v[74:75], v[44:45], v[8:9]
	v_pk_fma_f32 v[58:59], v[76:77], v[58:59], v[14:15]
	v_pk_fma_f32 v[56:57], v[78:79], v[56:57], v[12:13]
	v_pk_fma_f32 v[62:63], v[80:81], v[62:63], v[18:19]
	v_pk_fma_f32 v[60:61], v[82:83], v[60:61], v[16:17]
	v_pk_fma_f32 v[34:35], v[84:85], v[34:35], v[22:23]
	v_pk_fma_f32 v[32:33], v[86:87], v[32:33], v[20:21]
	v_pk_fma_f32 v[38:39], v[88:89], v[38:39], v[26:27]
	v_pk_fma_f32 v[36:37], v[90:91], v[36:37], v[24:25]
	v_pk_fma_f32 v[42:43], v[92:93], v[42:43], v[30:31]
	v_pk_fma_f32 v[40:41], v[94:95], v[40:41], v[28:29]
	v_cvt_pk_bf16_f32 v52, v52, v53
	v_cvt_pk_bf16_f32 v53, v54, v55
	v_cvt_pk_bf16_f32 v48, v48, v49
	v_cvt_pk_bf16_f32 v49, v50, v51
	v_cvt_pk_bf16_f32 v44, v44, v45
	v_cvt_pk_bf16_f32 v45, v46, v47
	v_cvt_pk_bf16_f32 v46, v56, v57
	v_cvt_pk_bf16_f32 v47, v58, v59
	v_cvt_pk_bf16_f32 v50, v60, v61
	v_cvt_pk_bf16_f32 v51, v62, v63
	v_cvt_pk_bf16_f32 v32, v32, v33
	v_cvt_pk_bf16_f32 v33, v34, v35
	v_cvt_pk_bf16_f32 v34, v36, v37
	v_cvt_pk_bf16_f32 v35, v38, v39
	v_cvt_pk_bf16_f32 v36, v40, v41
	v_cvt_pk_bf16_f32 v37, v42, v43
	global_store_dwordx2 v[96:97], v[52:53], off
	global_store_dwordx2 v[96:97], v[48:49], off offset:512
	global_store_dwordx2 v[96:97], v[44:45], off offset:1024
	global_store_dwordx2 v[96:97], v[46:47], off offset:1536
	global_store_dwordx2 v[96:97], v[50:51], off offset:2048
	global_store_dwordx2 v[96:97], v[32:33], off offset:2560
	global_store_dwordx2 v[96:97], v[34:35], off offset:3072
	global_store_dwordx2 v[96:97], v[36:37], off offset:3584
	v_lshl_add_u64 v[96:97], v[96:97], 0, s[14:15]
	s_cbranch_scc1 .LBB0_149

; __device__ __forceinline__ float wave_sum(float v) {
; #pragma unroll
;     for (int o = 1; o < 64; o <<= 1) v += __shfl_xor(v, o);
;     return v;
; __device__ __forceinline__ void row_phase(const Params& p, const int li_post, const int li_pre, const int gw, const int ngw, const int lane) {
;     ...
;     for (int i = i0; i < SEQ; i += istep) {
;         const int row = b * SEQ + i;
;         f32x4 v[8];
; #pragma unroll
;         for (int j = 0; j < 8; ++j) {
;             if (li_post <= 0) v[j] = *(const f32x4*)(p.x + (size_t)row * DM + j * 256 + lane * 4);
;             else { const u32x2 xx = *(const u32x2*)((const bf16_t*)(p.out + (size_t)row * DM) + j * 256 + lane * 4); v[j] = (f32x4){bflo(xx.x), bfhi(xx.x), bflo(xx.y), bfhi(xx.y)}; }
;         }
;         if (li_post >= 0) {
;             f32x4 y[8]; float ss = 0.f;
; #pragma unroll
;             for (int j = 0; j < 8; ++j) { const u32x2 yy = *(const u32x2*)(Y + (size_t)row * DM + j * 256 + lane * 4); y[j] = (f32x4){bflo(yy.x), bfhi(yy.x), bflo(yy.y), bfhi(yy.y)}; ss += (y[j][0] * y[j][0] + y[j][1] * y[j][1]) + (y[j][2] * y[j][2] + y[j][3] * y[j][3]); }
;             ss = wave_sum(ss);
.LBB0_447:
	v_lshl_add_u64 v[134:135], s[6:7], 0, v[128:129]
	v_add_co_u32_e32 v140, vcc, 0x19800000, v134
	v_add_co_u32_e64 v136, s[2:3], s5, v134
	s_nop 0
	v_addc_co_u32_e32 v141, vcc, 0, v135, vcc
	global_load_dwordx4 v[60:63], v[130:131], off offset:-4096
	global_load_dwordx4 v[56:59], v[130:131], off offset:-3072
	global_load_dwordx4 v[52:55], v[130:131], off offset:-2048
	global_load_dwordx4 v[48:51], v[130:131], off offset:-1024
	global_load_dwordx4 v[44:47], v[130:131], off
	global_load_dwordx4 v[40:43], v[130:131], off offset:1024
	global_load_dwordx4 v[36:39], v[130:131], off offset:2048
	global_load_dwordx4 v[32:35], v[130:131], off offset:3072
	v_addc_co_u32_e64 v137, s[2:3], 0, v135, s[2:3]
	global_load_dwordx2 v[134:135], v[140:141], off
	global_load_dwordx2 v[142:143], v[140:141], off offset:512
	global_load_dwordx2 v[144:145], v[140:141], off offset:1024
	global_load_dwordx2 v[146:147], v[140:141], off offset:1536
	global_load_dwordx2 v[148:149], v[140:141], off offset:2048
	global_load_dwordx2 v[150:151], v[140:141], off offset:2560
	global_load_dwordx2 v[152:153], v[140:141], off offset:3072
	s_nop 0
	global_load_dwordx2 v[140:141], v[140:141], off offset:3584
	v_lshl_add_u64 v[132:133], s[12:13], 0, v[128:129]
	s_add_i32 s0, s0, s4
	s_add_u32 s6, s6, s8
	s_addc_u32 s7, s7, s9
	s_add_u32 s12, s12, s10
	s_addc_u32 s13, s13, s11
	v_lshl_add_u64 v[130:131], v[130:131], 0, s[10:11]
	s_cmpk_lt_i32 s0, 0x2000
	s_waitcnt vmcnt(7)
	v_lshlrev_b32_e32 v154, 16, v134
	v_and_b32_e32 v155, 0xffff0000, v134
	v_lshlrev_b32_e32 v134, 16, v135
	v_and_b32_e32 v135, 0xffff0000, v135
	s_waitcnt vmcnt(6)
	v_lshlrev_b32_e32 v157, 16, v143
	v_lshlrev_b32_e32 v156, 16, v142
	v_and_b32_e32 v143, 0xffff0000, v143
	v_and_b32_e32 v142, 0xffff0000, v142
	s_waitcnt vmcnt(5)
	v_and_b32_e32 v159, 0xffff0000, v144
	s_waitcnt vmcnt(4)
	v_lshlrev_b32_e32 v161, 16, v146
	s_waitcnt vmcnt(0)
	v_lshlrev_b32_e32 v171, 16, v140
	v_mul_f32_e32 v160, v135, v135
	v_pk_mul_f32 v[174:175], v[142:143], v[142:143]
	v_mul_f32_e32 v170, v155, v155
	v_lshlrev_b32_e32 v158, 16, v144
	v_lshlrev_b32_e32 v144, 16, v145
	v_and_b32_e32 v145, 0xffff0000, v145
	v_mov_b32_e32 v177, v161
	v_mul_f32_e32 v176, v159, v159
	v_mov_b32_e32 v188, v156
	v_mov_b32_e32 v189, v142
	v_mov_b32_e32 v142, v157
	v_pk_fma_f32 v[194:195], v[134:135], v[134:135], v[160:161] op_sel_hi:[1,1,0]
	v_pk_fma_f32 v[156:157], v[156:157], v[156:157], v[174:175]
	v_pk_fma_f32 v[174:175], v[154:155], v[154:155], v[170:171] op_sel_hi:[1,1,0]
	v_and_b32_e32 v163, 0xffff0000, v146
	v_lshlrev_b32_e32 v146, 16, v147
	v_and_b32_e32 v147, 0xffff0000, v147
	v_mul_f32_e32 v178, v145, v145
	v_mov_b32_e32 v179, v171
	v_pk_fma_f32 v[196:197], v[158:159], v[158:159], v[176:177] op_sel_hi:[1,1,0]
	v_mov_b32_e32 v160, v174
	v_mov_b32_e32 v176, v194
	v_mul_f32_e32 v185, v163, v163
	v_mul_f32_e32 v187, v146, v146
	v_mul_f32_e32 v200, v147, v147
	v_mov_b32_e32 v162, v161
	v_pk_fma_f32 v[198:199], v[144:145], v[144:145], v[178:179] op_sel_hi:[1,1,0]
	v_pk_add_f32 v[174:175], v[174:175], v[194:195]
	v_pk_add_f32 v[156:157], v[156:157], v[156:157] op_sel:[0,1] op_sel_hi:[1,0]
	v_pk_mul_f32 v[160:161], v[160:161], v[176:177]
	v_lshlrev_b32_e32 v165, 16, v149
	v_lshlrev_b32_e32 v164, 16, v148
	v_and_b32_e32 v149, 0xffff0000, v149
	v_and_b32_e32 v148, 0xffff0000, v148
	v_mov_b32_e32 v197, v187
	v_mov_b32_e32 v199, v200
	v_mov_b32_e32 v157, v185
	v_mov_b32_e32 v175, v161
	v_pk_mul_f32 v[180:181], v[148:149], v[148:149]
	v_pk_add_f32 v[176:177], v[196:197], v[198:199]
	v_pk_add_f32 v[156:157], v[174:175], v[156:157]
	v_lshlrev_b32_e32 v167, 16, v151
	v_lshlrev_b32_e32 v166, 16, v150
	v_and_b32_e32 v151, 0xffff0000, v151
	v_and_b32_e32 v150, 0xffff0000, v150
	v_mov_b32_e32 v190, v164
	v_mov_b32_e32 v191, v148
	v_mov_b32_e32 v148, v165
	v_pk_fma_f32 v[164:165], v[164:165], v[164:165], v[180:181]
	v_pk_add_f32 v[156:157], v[156:157], v[176:177]
	v_lshlrev_b32_e32 v168, 16, v152
	v_and_b32_e32 v169, 0xffff0000, v152
	v_lshlrev_b32_e32 v152, 16, v153
	v_and_b32_e32 v153, 0xffff0000, v153
	v_pk_mul_f32 v[182:183], v[150:151], v[150:151]
	v_pk_add_f32 v[164:165], v[164:165], v[164:165] op_sel:[0,1] op_sel_hi:[1,0]
	v_pk_add_f32 v[156:157], v[156:157], v[156:157] op_sel:[0,1] op_sel_hi:[1,0]
	v_and_b32_e32 v173, 0xffff0000, v140
	v_lshlrev_b32_e32 v140, 16, v141
	v_and_b32_e32 v141, 0xffff0000, v141
	v_mul_f32_e32 v184, v169, v169
	v_mul_f32_e32 v186, v153, v153
	v_mov_b32_e32 v192, v166
	v_mov_b32_e32 v193, v150
	v_mov_b32_e32 v150, v167
	v_pk_fma_f32 v[166:167], v[166:167], v[166:167], v[182:183]
	v_mov_b32_e32 v178, v164
	v_mov_b32_e32 v170, v156
	v_mul_f32_e32 v201, v173, v173
	v_mul_f32_e32 v202, v140, v140
	v_mul_f32_e32 v203, v141, v141
	v_pk_fma_f32 v[180:181], v[168:169], v[168:169], v[184:185] op_sel_hi:[1,1,0]
	v_pk_fma_f32 v[182:183], v[152:153], v[152:153], v[186:187] op_sel_hi:[1,1,0]
	v_pk_add_f32 v[166:167], v[166:167], v[166:167] op_sel:[0,1] op_sel_hi:[1,0]
	v_pk_add_f32 v[156:157], v[156:157], v[164:165]
	v_pk_mul_f32 v[160:161], v[170:171], v[178:179]
	v_mov_b32_e32 v181, v202
	v_mov_b32_e32 v183, v203
	v_mov_b32_e32 v167, v201
	v_mov_b32_e32 v157, v161
	v_pk_add_f32 v[180:181], v[180:181], v[182:183]
	v_pk_add_f32 v[156:157], v[156:157], v[166:167]
	v_mov_b32_e32 v172, v171
	v_pk_add_f32 v[156:157], v[156:157], v[180:181]
	s_nop 0
	v_add_f32_e32 v156, v156, v157
	s_nop 1
	v_add_f32_dpp v157, v156, v156 quad_perm:[1,0,3,2] row_mask:0xf bank_mask:0xf
	s_nop 1
	v_add_f32_dpp v156, v157, v157 quad_perm:[2,3,0,1] row_mask:0xf bank_mask:0xf
	s_nop 1
	v_add_f32_dpp v157, v156, v156 row_half_mirror row_mask:0xf bank_mask:0xf
; __device__ __forceinline__ unsigned pk2(float lo, float hi) { f32x2 v = {lo, hi}; bf16x2_t b = __builtin_convertvector(v, bf16x2_t); return __builtin_bit_cast(unsigned, b); }
; __device__ __forceinline__ float wave_sum(float v) {
; #pragma unroll
;     for (int o = 1; o < 64; o <<= 1) v += __shfl_xor(v, o);
;     return v;
; __device__ __forceinline__ void row_phase(const Params& p, const int li_post, const int li_pre, const int gw, const int ngw, const int lane) {
;     ...
;             ss = wave_sum(ss);
;             const float r = 1.0f / sqrtf(ss * (1.0f / DM) + EPS);
; #pragma unroll
;             for (int j = 0; j < 8; ++j) { const int col = j * 256 + lane * 4;
;                 v[j] = v[j] + (y[j] * r) * GP[j];
;                 if (li_post == 3) *(f32x4*)(p.out + (size_t)row * DM + col) = v[j];
;                 else { u32x2 w; w.x = pk2(v[j][0], v[j][1]); w.y = pk2(v[j][2], v[j][3]); *(u32x2*)((bf16_t*)(p.out + (size_t)row * DM) + col) = w; } }
;         }
;         if (li_pre >= 0) {
;             float ss = 0.f;
; #pragma unroll
;             for (int j = 0; j < 8; ++j) ss += (v[j][0] * v[j][0] + v[j][1] * v[j][1]) + (v[j][2] * v[j][2] + v[j][3] * v[j][3]);
	s_nop 1
	v_add_f32_dpp v156, v157, v157 row_mirror row_mask:0xf bank_mask:0xf
	v_mov_b32_e32 v157, v156
	s_nop 1
	v_permlane16_swap_b32_e32 v156, v157
	s_nop 1
	v_add_f32_e32 v156, v156, v157
	v_mov_b32_e32 v157, v156
	s_nop 1
	v_permlane32_swap_b32_e32 v156, v157
	s_nop 1
	v_add_f32_e32 v156, v156, v157
	v_fmamk_f32 v156, v156, 0x3a000000, v138
	v_mul_f32_e32 v157, 0x4f800000, v156
	v_cmp_gt_f32_e32 vcc, s1, v156
	s_nop 1
	v_cndmask_b32_e32 v156, v156, v157, vcc
	v_sqrt_f32_e32 v157, v156
	s_nop 0
	v_add_u32_e32 v160, -1, v157
	v_add_u32_e32 v161, 1, v157
	v_fma_f32 v164, -v160, v157, v156
	v_fma_f32 v165, -v161, v157, v156
	v_cmp_ge_f32_e64 s[2:3], 0, v164
	s_nop 1
	v_cndmask_b32_e64 v157, v157, v160, s[2:3]
	v_cmp_lt_f32_e64 s[2:3], 0, v165
	s_nop 1
	v_cndmask_b32_e64 v157, v157, v161, s[2:3]
	v_mul_f32_e32 v160, 0x37800000, v157
	v_cndmask_b32_e32 v157, v157, v160, vcc
	v_cmp_class_f32_e32 vcc, v156, v139
	s_nop 1
	v_cndmask_b32_e32 v156, v157, v156, vcc
	v_div_scale_f32 v157, s[2:3], v156, v156, 1.0
	v_rcp_f32_e32 v161, v157
	v_div_scale_f32 v160, vcc, 1.0, v156, 1.0
	v_fma_f32 v164, -v157, v161, 1.0
	v_fmac_f32_e32 v161, v164, v161
	v_mul_f32_e32 v164, v160, v161
	v_fma_f32 v165, -v157, v164, v160
	v_fmac_f32_e32 v164, v165, v161
	v_fma_f32 v157, -v157, v164, v160
	v_div_fmas_f32 v157, v157, v161, v164
	v_div_fixup_f32 v156, v157, v156, 1.0
	v_pk_mul_f32 v[154:155], v[156:157], v[154:155] op_sel_hi:[0,1]
	v_pk_mul_f32 v[134:135], v[156:157], v[134:135] op_sel_hi:[0,1]
	v_pk_mul_f32 v[160:161], v[156:157], v[188:189] op_sel_hi:[0,1]
	v_pk_mul_f32 v[142:143], v[156:157], v[142:143] op_sel_hi:[0,1]
	v_pk_mul_f32 v[158:159], v[156:157], v[158:159] op_sel_hi:[0,1]
	v_pk_mul_f32 v[144:145], v[156:157], v[144:145] op_sel_hi:[0,1]
	v_pk_mul_f32 v[162:163], v[162:163], v[156:157] op_sel_hi:[1,0]
	v_pk_mul_f32 v[146:147], v[146:147], v[156:157] op_sel_hi:[1,0]
	v_pk_mul_f32 v[164:165], v[156:157], v[190:191] op_sel_hi:[0,1]
	v_pk_mul_f32 v[148:149], v[156:157], v[148:149] op_sel_hi:[0,1]
	v_pk_mul_f32 v[166:167], v[156:157], v[192:193] op_sel_hi:[0,1]
	v_pk_mul_f32 v[150:151], v[156:157], v[150:151] op_sel_hi:[0,1]
	v_pk_mul_f32 v[168:169], v[156:157], v[168:169] op_sel_hi:[0,1]
	v_pk_mul_f32 v[152:153], v[156:157], v[152:153] op_sel_hi:[0,1]
	v_pk_mul_f32 v[170:171], v[172:173], v[156:157] op_sel_hi:[1,0]
	v_pk_mul_f32 v[140:141], v[140:141], v[156:157] op_sel_hi:[1,0]
	v_pk_fma_f32 v[62:63], v[64:65], v[134:135], v[62:63]
	v_pk_fma_f32 v[60:61], v[66:67], v[154:155], v[60:61]
	v_pk_fma_f32 v[58:59], v[68:69], v[142:143], v[58:59]
	v_pk_fma_f32 v[56:57], v[70:71], v[160:161], v[56:57]
	v_pk_fma_f32 v[54:55], v[72:73], v[144:145], v[54:55]
	v_pk_fma_f32 v[52:53], v[74:75], v[158:159], v[52:53]
	v_pk_fma_f32 v[50:51], v[76:77], v[146:147], v[50:51]
	v_pk_fma_f32 v[48:49], v[78:79], v[162:163], v[48:49]
	v_pk_fma_f32 v[46:47], v[80:81], v[148:149], v[46:47]
	v_pk_fma_f32 v[44:45], v[82:83], v[164:165], v[44:45]
	v_pk_fma_f32 v[42:43], v[84:85], v[150:151], v[42:43]
	v_pk_fma_f32 v[40:41], v[86:87], v[166:167], v[40:41]
	v_pk_fma_f32 v[38:39], v[112:113], v[152:153], v[38:39]
	v_pk_fma_f32 v[36:37], v[114:115], v[168:169], v[36:37]
	v_pk_fma_f32 v[34:35], v[120:121], v[140:141], v[34:35]
	v_pk_fma_f32 v[32:33], v[122:123], v[170:171], v[32:33]
	v_cvt_pk_bf16_f32 v134, v60, v61
	v_cvt_pk_bf16_f32 v135, v62, v63
	v_mov_b32_e32 v156, v61
	v_mov_b32_e32 v157, v57
	v_mov_b32_e32 v160, v63
	v_mov_b32_e32 v161, v59
	v_cvt_pk_bf16_f32 v140, v56, v57
	v_cvt_pk_bf16_f32 v141, v58, v59
	v_cvt_pk_bf16_f32 v142, v52, v53
	v_cvt_pk_bf16_f32 v143, v54, v55
	v_cvt_pk_bf16_f32 v144, v48, v49
	v_cvt_pk_bf16_f32 v145, v50, v51
	v_cvt_pk_bf16_f32 v146, v44, v45
	v_cvt_pk_bf16_f32 v147, v46, v47
	v_cvt_pk_bf16_f32 v148, v40, v41
	v_cvt_pk_bf16_f32 v149, v42, v43
	v_cvt_pk_bf16_f32 v150, v36, v37
	v_cvt_pk_bf16_f32 v151, v38, v39
	v_cvt_pk_bf16_f32 v152, v32, v33
	v_cvt_pk_bf16_f32 v153, v34, v35
	v_mov_b32_e32 v154, v60
	v_mov_b32_e32 v155, v56
	v_mov_b32_e32 v158, v62
	v_mov_b32_e32 v159, v58
	v_pk_mul_f32 v[162:163], v[54:55], v[54:55]
	v_pk_mul_f32 v[164:165], v[52:53], v[52:53]
	global_store_dwordx2 v[132:133], v[134:135], off
	global_store_dwordx2 v[132:133], v[140:141], off offset:512
	global_store_dwordx2 v[132:133], v[142:143], off offset:1024
	global_store_dwordx2 v[132:133], v[144:145], off offset:1536
	global_store_dwordx2 v[132:133], v[146:147], off offset:2048
	global_store_dwordx2 v[132:133], v[148:149], off offset:2560
	global_store_dwordx2 v[132:133], v[150:151], off offset:3072
	global_store_dwordx2 v[132:133], v[152:153], off offset:3584
	v_pk_mul_f32 v[132:133], v[156:157], v[156:157]
	v_pk_mul_f32 v[134:135], v[160:161], v[160:161]
	v_pk_mov_b32 v[140:141], v[164:165], v[162:163] op_sel:[1,0]
	v_mov_b32_e32 v165, v163
	v_pk_fma_f32 v[132:133], v[154:155], v[154:155], v[132:133]
	v_pk_fma_f32 v[134:135], v[158:159], v[158:159], v[134:135]
	v_mul_f32_e32 v166, v48, v48
	v_mul_f32_e32 v168, v50, v50
	v_pk_add_f32 v[140:141], v[140:141], v[164:165]
	v_pk_add_f32 v[132:133], v[132:133], v[134:135]
	v_pk_fma_f32 v[142:143], v[48:49], v[48:49], v[166:167] op_sel_hi:[1,1,0]
	v_pk_fma_f32 v[144:145], v[50:51], v[50:51], v[168:169] op_sel_hi:[1,1,0]
	v_pk_add_f32 v[134:135], v[140:141], v[140:141] op_sel_hi:[0,1]
	v_pk_add_f32 v[132:133], v[132:133], v[132:133] op_sel_hi:[0,1]
	v_pk_mul_f32 v[170:171], v[42:43], v[42:43]
	v_pk_mul_f32 v[172:173], v[40:41], v[40:41]
	v_mul_f32_e32 v142, v44, v44
	v_mul_f32_e32 v144, v45, v45
; __device__ __forceinline__ unsigned pk2(float lo, float hi) { f32x2 v = {lo, hi}; bf16x2_t b = __builtin_convertvector(v, bf16x2_t); return __builtin_bit_cast(unsigned, b); }
; __device__ __forceinline__ float wave_sum(float v) {
; #pragma unroll
;     for (int o = 1; o < 64; o <<= 1) v += __shfl_xor(v, o);
;     return v;
; __device__ __forceinline__ void row_phase(const Params& p, const int li_post, const int li_pre, const int gw, const int ngw, const int lane) {
;     ...
;             for (int j = 0; j < 8; ++j) ss += (v[j][0] * v[j][0] + v[j][1] * v[j][1]) + (v[j][2] * v[j][2] + v[j][3] * v[j][3]);
;             ss = wave_sum(ss);
;             const float r = 1.0f / sqrtf(ss * (1.0f / DM) + EPS);
; #pragma unroll
;             for (int j = 0; j < 8; ++j) { const int col = j * 256 + lane * 4;
;                 const f32x4 h = (v[j] * r) * PA[j] + SH[j];
;                 u32x2 w; w.x = pk2(h[0], h[1]); w.y = pk2(h[2], h[3]);
;                 *(u32x2*)(H + (size_t)row * DM + col) = w; }
	v_mul_f32_e32 v134, v46, v46
	v_mul_f32_e32 v132, v47, v47
	v_pk_mov_b32 v[146:147], v[172:173], v[170:171] op_sel:[1,0]
	v_mov_b32_e32 v173, v171
	v_pk_add_f32 v[140:141], v[142:143], v[144:145]
	v_pk_add_f32 v[132:133], v[134:135], v[132:133]
	v_mul_f32_e32 v174, v36, v36
	v_mul_f32_e32 v176, v38, v38
	v_pk_add_f32 v[146:147], v[146:147], v[172:173]
	v_pk_add_f32 v[132:133], v[140:141], v[132:133]
	v_pk_fma_f32 v[148:149], v[36:37], v[36:37], v[174:175] op_sel_hi:[1,1,0]
	v_pk_fma_f32 v[150:151], v[38:39], v[38:39], v[176:177] op_sel_hi:[1,1,0]
	v_pk_add_f32 v[142:143], v[146:147], v[146:147] op_sel_hi:[0,1]
	v_pk_add_f32 v[132:133], v[132:133], v[132:133] op_sel_hi:[0,1]
	v_mul_f32_e32 v148, v32, v32
	v_mul_f32_e32 v150, v33, v33
	v_mul_f32_e32 v142, v34, v34
	v_mul_f32_e32 v132, v35, v35
	v_pk_add_f32 v[144:145], v[148:149], v[150:151]
	v_pk_add_f32 v[132:133], v[142:143], v[132:133]
	s_nop 0
	v_pk_add_f32 v[132:133], v[144:145], v[132:133]
	s_nop 0
	v_add_f32_e32 v132, v132, v133
	s_nop 1
	v_add_f32_dpp v133, v132, v132 quad_perm:[1,0,3,2] row_mask:0xf bank_mask:0xf
	s_nop 1
	v_add_f32_dpp v132, v133, v133 quad_perm:[2,3,0,1] row_mask:0xf bank_mask:0xf
	s_nop 1
	v_add_f32_dpp v133, v132, v132 row_half_mirror row_mask:0xf bank_mask:0xf
	s_nop 1
	v_add_f32_dpp v132, v133, v133 row_mirror row_mask:0xf bank_mask:0xf
	v_mov_b32_e32 v133, v132
	s_nop 1
	v_permlane16_swap_b32_e32 v132, v133
	s_nop 1
	v_add_f32_e32 v132, v132, v133
	v_mov_b32_e32 v133, v132
	s_nop 1
	v_permlane32_swap_b32_e32 v132, v133
	s_nop 1
	v_add_f32_e32 v132, v132, v133
	v_fmamk_f32 v132, v132, 0x3a000000, v138
	v_mul_f32_e32 v133, 0x4f800000, v132
	v_cmp_gt_f32_e32 vcc, s1, v132
	s_nop 1
	v_cndmask_b32_e32 v132, v132, v133, vcc
	v_sqrt_f32_e32 v133, v132
	s_nop 0
	v_add_u32_e32 v134, -1, v133
	v_add_u32_e32 v135, 1, v133
	v_fma_f32 v140, -v134, v133, v132
	v_fma_f32 v141, -v135, v133, v132
	v_cmp_ge_f32_e64 s[2:3], 0, v140
	s_nop 1
	v_cndmask_b32_e64 v133, v133, v134, s[2:3]
	v_cmp_lt_f32_e64 s[2:3], 0, v141
	s_nop 1
	v_cndmask_b32_e64 v133, v133, v135, s[2:3]
	v_mul_f32_e32 v134, 0x37800000, v133
	v_cndmask_b32_e32 v133, v133, v134, vcc
	v_cmp_class_f32_e32 vcc, v132, v139
	s_nop 1
	v_cndmask_b32_e32 v132, v133, v132, vcc
	v_div_scale_f32 v133, s[2:3], v132, v132, 1.0
	v_rcp_f32_e32 v135, v133
	v_div_scale_f32 v134, vcc, 1.0, v132, 1.0
	v_fma_f32 v140, -v133, v135, 1.0
	v_fmac_f32_e32 v135, v140, v135
	v_mul_f32_e32 v140, v134, v135
	v_fma_f32 v141, -v133, v140, v134
	v_fmac_f32_e32 v140, v141, v135
	v_fma_f32 v133, -v133, v140, v134
	v_div_fmas_f32 v133, v133, v135, v140
	v_div_fixup_f32 v132, v133, v132, 1.0
	v_pk_mul_f32 v[60:61], v[60:61], v[132:133] op_sel_hi:[1,0]
	v_pk_mul_f32 v[62:63], v[62:63], v[132:133] op_sel_hi:[1,0]
	v_pk_mul_f32 v[56:57], v[56:57], v[132:133] op_sel_hi:[1,0]
	v_pk_mul_f32 v[58:59], v[58:59], v[132:133] op_sel_hi:[1,0]
	v_pk_mul_f32 v[52:53], v[52:53], v[132:133] op_sel_hi:[1,0]
	v_pk_mul_f32 v[54:55], v[54:55], v[132:133] op_sel_hi:[1,0]
	v_pk_mul_f32 v[48:49], v[48:49], v[132:133] op_sel_hi:[1,0]
	v_pk_mul_f32 v[50:51], v[50:51], v[132:133] op_sel_hi:[1,0]
	v_pk_mul_f32 v[44:45], v[44:45], v[132:133] op_sel_hi:[1,0]
	v_pk_mul_f32 v[46:47], v[46:47], v[132:133] op_sel_hi:[1,0]
	v_pk_mul_f32 v[40:41], v[40:41], v[132:133] op_sel_hi:[1,0]
	v_pk_mul_f32 v[42:43], v[42:43], v[132:133] op_sel_hi:[1,0]
	v_pk_mul_f32 v[36:37], v[36:37], v[132:133] op_sel_hi:[1,0]
	v_pk_mul_f32 v[38:39], v[38:39], v[132:133] op_sel_hi:[1,0]
	v_pk_mul_f32 v[32:33], v[32:33], v[132:133] op_sel_hi:[1,0]
	v_pk_mul_f32 v[34:35], v[34:35], v[132:133] op_sel_hi:[1,0]
	v_pk_fma_f32 v[62:63], v[88:89], v[62:63], v[18:19]
	v_pk_fma_f32 v[60:61], v[90:91], v[60:61], v[16:17]
	v_pk_fma_f32 v[58:59], v[92:93], v[58:59], v[22:23]
	v_pk_fma_f32 v[56:57], v[94:95], v[56:57], v[20:21]
	v_pk_fma_f32 v[54:55], v[96:97], v[54:55], v[26:27]
	v_pk_fma_f32 v[52:53], v[98:99], v[52:53], v[24:25]
	v_pk_fma_f32 v[50:51], v[100:101], v[50:51], v[30:31]
	v_pk_fma_f32 v[48:49], v[102:103], v[48:49], v[28:29]
	v_pk_fma_f32 v[46:47], v[104:105], v[46:47], v[2:3]
	v_pk_fma_f32 v[44:45], v[106:107], v[44:45], v[0:1]
	v_pk_fma_f32 v[42:43], v[108:109], v[42:43], v[6:7]
	v_pk_fma_f32 v[40:41], v[110:111], v[40:41], v[4:5]
	v_pk_fma_f32 v[38:39], v[116:117], v[38:39], v[10:11]
	v_pk_fma_f32 v[36:37], v[118:119], v[36:37], v[8:9]
	v_pk_fma_f32 v[34:35], v[124:125], v[34:35], v[14:15]
	v_pk_fma_f32 v[32:33], v[126:127], v[32:33], v[12:13]
	v_cvt_pk_bf16_f32 v60, v60, v61
	v_cvt_pk_bf16_f32 v61, v62, v63
	v_cvt_pk_bf16_f32 v56, v56, v57
	v_cvt_pk_bf16_f32 v57, v58, v59
	v_cvt_pk_bf16_f32 v52, v52, v53
	v_cvt_pk_bf16_f32 v53, v54, v55
	v_cvt_pk_bf16_f32 v48, v48, v49
	v_cvt_pk_bf16_f32 v49, v50, v51
	v_cvt_pk_bf16_f32 v44, v44, v45
	v_cvt_pk_bf16_f32 v45, v46, v47
	v_cvt_pk_bf16_f32 v40, v40, v41
	v_cvt_pk_bf16_f32 v41, v42, v43
	v_cvt_pk_bf16_f32 v36, v36, v37
	v_cvt_pk_bf16_f32 v37, v38, v39
	v_cvt_pk_bf16_f32 v32, v32, v33
	v_cvt_pk_bf16_f32 v33, v34, v35
	global_store_dwordx2 v[136:137], v[60:61], off
	global_store_dwordx2 v[136:137], v[56:57], off offset:512
	global_store_dwordx2 v[136:137], v[52:53], off offset:1024
	global_store_dwordx2 v[136:137], v[48:49], off offset:1536
	global_store_dwordx2 v[136:137], v[44:45], off offset:2048
	global_store_dwordx2 v[136:137], v[40:41], off offset:2560
	global_store_dwordx2 v[136:137], v[36:37], off offset:3072
	global_store_dwordx2 v[136:137], v[32:33], off offset:3584
	s_cbranch_scc1 .LBB0_447

; __device__ __forceinline__ void row_phase(const Params& p, const int li_post, const int li_pre, const int gw, const int ngw, const int lane) {
;     ...
;     for (int i = i0; i < SEQ; i += istep) {
;         const int row = b * SEQ + i;
;         f32x4 v[8];
; #pragma unroll
;         for (int j = 0; j < 8; ++j) {
;             if (li_post <= 0) v[j] = *(const f32x4*)(p.x + (size_t)row * DM + j * 256 + lane * 4);
;             else { const u32x2 xx = *(const u32x2*)((const bf16_t*)(p.out + (size_t)row * DM) + j * 256 + lane * 4); v[j] = (f32x4){bflo(xx.x), bfhi(xx.x), bflo(xx.y), bfhi(xx.y)}; }
;         }
;         if (li_post >= 0) {
;             f32x4 y[8]; float ss = 0.f;
; #pragma unroll
;             for (int j = 0; j < 8; ++j) { const u32x2 yy = *(const u32x2*)(Y + (size_t)row * DM + j * 256 + lane * 4); y[j] = (f32x4){bflo(yy.x), bfhi(yy.x), bflo(yy.y), bfhi(yy.y)}; ss += (y[j][0] * y[j][0] + y[j][1] * y[j][1]) + (y[j][2] * y[j][2] + y[j][3] * y[j][3]); }
;             ss = wave_sum(ss);
.LBB0_757:
	v_lshl_add_u64 v[100:101], s[6:7], 0, v[96:97]
	v_add_co_u32_e32 v120, vcc, s1, v100
	v_lshl_add_u64 v[98:99], s[10:11], 0, v[96:97]
	s_nop 0
	v_addc_co_u32_e32 v121, vcc, 0, v101, vcc
	global_load_dwordx2 v[104:105], v[98:99], off
	global_load_dwordx2 v[106:107], v[98:99], off offset:512
	global_load_dwordx2 v[108:109], v[98:99], off offset:1024
	global_load_dwordx2 v[110:111], v[98:99], off offset:1536
	global_load_dwordx2 v[112:113], v[98:99], off offset:2048
	global_load_dwordx2 v[114:115], v[98:99], off offset:2560
	global_load_dwordx2 v[116:117], v[98:99], off offset:3072
	global_load_dwordx2 v[118:119], v[98:99], off offset:3584
	global_load_dwordx2 v[122:123], v[120:121], off
	global_load_dwordx2 v[124:125], v[120:121], off offset:512
	global_load_dwordx2 v[126:127], v[120:121], off offset:1024
	global_load_dwordx2 v[128:129], v[120:121], off offset:1536
	global_load_dwordx2 v[130:131], v[120:121], off offset:2048
	global_load_dwordx2 v[132:133], v[120:121], off offset:2560
	global_load_dwordx2 v[134:135], v[120:121], off offset:3072
	s_nop 0
	global_load_dwordx2 v[120:121], v[120:121], off offset:3584
	v_add_co_u32_e32 v100, vcc, s14, v100
	s_add_i32 s0, s0, s4
	s_nop 0
	v_addc_co_u32_e32 v101, vcc, 0, v101, vcc
	s_add_u32 s6, s6, s8
	s_addc_u32 s7, s7, s9
	s_add_u32 s10, s10, s12
	s_addc_u32 s11, s11, s13
	s_cmpk_lt_i32 s0, 0x2000
	s_waitcnt vmcnt(15)
	v_lshlrev_b32_e32 v136, 16, v104
	s_waitcnt vmcnt(7)
	v_lshlrev_b32_e32 v152, 16, v122
	v_and_b32_e32 v153, 0xffff0000, v122
	v_lshlrev_b32_e32 v122, 16, v123
	v_and_b32_e32 v123, 0xffff0000, v123
	s_waitcnt vmcnt(6)
	v_lshlrev_b32_e32 v155, 16, v125
	v_lshlrev_b32_e32 v154, 16, v124
	v_and_b32_e32 v125, 0xffff0000, v125
	v_and_b32_e32 v124, 0xffff0000, v124
	s_waitcnt vmcnt(5)
	v_and_b32_e32 v157, 0xffff0000, v126
	s_waitcnt vmcnt(4)
	v_lshlrev_b32_e32 v159, 16, v128
	s_waitcnt vmcnt(0)
	v_lshlrev_b32_e32 v169, 16, v120
	v_mul_f32_e32 v158, v123, v123
	v_pk_mul_f32 v[172:173], v[124:125], v[124:125]
	v_mul_f32_e32 v168, v153, v153
	v_lshlrev_b32_e32 v156, 16, v126
	v_lshlrev_b32_e32 v126, 16, v127
	v_and_b32_e32 v127, 0xffff0000, v127
	v_mov_b32_e32 v175, v159
	v_mul_f32_e32 v174, v157, v157
	v_mov_b32_e32 v186, v154
	v_mov_b32_e32 v187, v124
	v_mov_b32_e32 v124, v155
	v_pk_fma_f32 v[192:193], v[122:123], v[122:123], v[158:159] op_sel_hi:[1,1,0]
	v_pk_fma_f32 v[154:155], v[154:155], v[154:155], v[172:173]
	v_pk_fma_f32 v[172:173], v[152:153], v[152:153], v[168:169] op_sel_hi:[1,1,0]
	v_and_b32_e32 v161, 0xffff0000, v128
	v_lshlrev_b32_e32 v128, 16, v129
	v_and_b32_e32 v129, 0xffff0000, v129
	v_mul_f32_e32 v176, v127, v127
	v_mov_b32_e32 v177, v169
	v_pk_fma_f32 v[194:195], v[156:157], v[156:157], v[174:175] op_sel_hi:[1,1,0]
	v_mov_b32_e32 v158, v172
	v_mov_b32_e32 v174, v192
	v_mul_f32_e32 v183, v161, v161
	v_mul_f32_e32 v185, v128, v128
	v_mul_f32_e32 v198, v129, v129
	v_mov_b32_e32 v160, v159
	v_pk_fma_f32 v[196:197], v[126:127], v[126:127], v[176:177] op_sel_hi:[1,1,0]
	v_pk_add_f32 v[172:173], v[172:173], v[192:193]
	v_pk_add_f32 v[154:155], v[154:155], v[154:155] op_sel:[0,1] op_sel_hi:[1,0]
	v_pk_mul_f32 v[158:159], v[158:159], v[174:175]
	v_lshlrev_b32_e32 v163, 16, v131
	v_lshlrev_b32_e32 v162, 16, v130
	v_and_b32_e32 v131, 0xffff0000, v131
	v_and_b32_e32 v130, 0xffff0000, v130
	v_mov_b32_e32 v195, v185
	v_mov_b32_e32 v197, v198
	v_mov_b32_e32 v155, v183
	v_mov_b32_e32 v173, v159
	v_pk_mul_f32 v[178:179], v[130:131], v[130:131]
	v_pk_add_f32 v[174:175], v[194:195], v[196:197]
	v_pk_add_f32 v[154:155], v[172:173], v[154:155]
	v_lshlrev_b32_e32 v165, 16, v133
	v_lshlrev_b32_e32 v164, 16, v132
	v_and_b32_e32 v133, 0xffff0000, v133
	v_and_b32_e32 v132, 0xffff0000, v132
	v_mov_b32_e32 v188, v162
	v_mov_b32_e32 v189, v130
	v_mov_b32_e32 v130, v163
	v_pk_fma_f32 v[162:163], v[162:163], v[162:163], v[178:179]
	v_pk_add_f32 v[154:155], v[154:155], v[174:175]
	v_lshlrev_b32_e32 v166, 16, v134
	v_and_b32_e32 v167, 0xffff0000, v134
	v_lshlrev_b32_e32 v134, 16, v135
	v_and_b32_e32 v135, 0xffff0000, v135
	v_pk_mul_f32 v[180:181], v[132:133], v[132:133]
	v_pk_add_f32 v[162:163], v[162:163], v[162:163] op_sel:[0,1] op_sel_hi:[1,0]
	v_pk_add_f32 v[154:155], v[154:155], v[154:155] op_sel:[0,1] op_sel_hi:[1,0]
	v_and_b32_e32 v171, 0xffff0000, v120
	v_lshlrev_b32_e32 v120, 16, v121
	v_and_b32_e32 v121, 0xffff0000, v121
	v_mul_f32_e32 v182, v167, v167
	v_mul_f32_e32 v184, v135, v135
	v_mov_b32_e32 v190, v164
	v_mov_b32_e32 v191, v132
	v_mov_b32_e32 v132, v165
	v_pk_fma_f32 v[164:165], v[164:165], v[164:165], v[180:181]
	v_mov_b32_e32 v176, v162
	v_mov_b32_e32 v168, v154
	v_mul_f32_e32 v199, v171, v171
	v_mul_f32_e32 v200, v120, v120
	v_mul_f32_e32 v201, v121, v121
	v_pk_fma_f32 v[178:179], v[166:167], v[166:167], v[182:183] op_sel_hi:[1,1,0]
	v_pk_fma_f32 v[180:181], v[134:135], v[134:135], v[184:185] op_sel_hi:[1,1,0]
	v_pk_add_f32 v[164:165], v[164:165], v[164:165] op_sel:[0,1] op_sel_hi:[1,0]
	v_pk_add_f32 v[154:155], v[154:155], v[162:163]
	v_pk_mul_f32 v[158:159], v[168:169], v[176:177]
	v_mov_b32_e32 v179, v200
	v_mov_b32_e32 v181, v201
	v_mov_b32_e32 v165, v199
	v_mov_b32_e32 v155, v159
	v_pk_add_f32 v[178:179], v[178:179], v[180:181]
	v_pk_add_f32 v[154:155], v[154:155], v[164:165]
	v_and_b32_e32 v137, 0xffff0000, v104
	v_pk_add_f32 v[154:155], v[154:155], v[178:179]
	v_lshlrev_b32_e32 v104, 16, v105
	v_add_f32_e32 v154, v154, v155
	v_and_b32_e32 v105, 0xffff0000, v105
	v_lshlrev_b32_e32 v138, 16, v106
	v_and_b32_e32 v139, 0xffff0000, v106
	v_lshlrev_b32_e32 v106, 16, v107
	v_and_b32_e32 v107, 0xffff0000, v107
	v_mov_b32_e32 v170, v169
	v_lshlrev_b32_e32 v140, 16, v108
; __device__ __forceinline__ unsigned pk2(float lo, float hi) { f32x2 v = {lo, hi}; bf16x2_t b = __builtin_convertvector(v, bf16x2_t); return __builtin_bit_cast(unsigned, b); }
; __device__ __forceinline__ float wave_sum(float v) {
; #pragma unroll
;     for (int o = 1; o < 64; o <<= 1) v += __shfl_xor(v, o);
;     return v;
; __device__ __forceinline__ void row_phase(const Params& p, const int li_post, const int li_pre, const int gw, const int ngw, const int lane) {
;     ...
;             for (int j = 0; j < 8; ++j) { const u32x2 yy = *(const u32x2*)(Y + (size_t)row * DM + j * 256 + lane * 4); y[j] = (f32x4){bflo(yy.x), bfhi(yy.x), bflo(yy.y), bfhi(yy.y)}; ss += (y[j][0] * y[j][0] + y[j][1] * y[j][1]) + (y[j][2] * y[j][2] + y[j][3] * y[j][3]); }
;             ss = wave_sum(ss);
;             const float r = 1.0f / sqrtf(ss * (1.0f / DM) + EPS);
; #pragma unroll
;             for (int j = 0; j < 8; ++j) { const int col = j * 256 + lane * 4;
;                 v[j] = v[j] + (y[j] * r) * GP[j];
;                 if (li_post == 3) *(f32x4*)(p.out + (size_t)row * DM + col) = v[j];
;                 else { u32x2 w; w.x = pk2(v[j][0], v[j][1]); w.y = pk2(v[j][2], v[j][3]); *(u32x2*)((bf16_t*)(p.out + (size_t)row * DM) + col) = w; } }
	v_and_b32_e32 v141, 0xffff0000, v108
	v_lshlrev_b32_e32 v108, 16, v109
	v_and_b32_e32 v109, 0xffff0000, v109
	v_lshlrev_b32_e32 v142, 16, v110
	v_and_b32_e32 v143, 0xffff0000, v110
	v_lshlrev_b32_e32 v110, 16, v111
	v_and_b32_e32 v111, 0xffff0000, v111
	v_lshlrev_b32_e32 v144, 16, v112
	v_and_b32_e32 v145, 0xffff0000, v112
	v_lshlrev_b32_e32 v112, 16, v113
	v_and_b32_e32 v113, 0xffff0000, v113
	v_lshlrev_b32_e32 v146, 16, v114
	v_and_b32_e32 v147, 0xffff0000, v114
	v_lshlrev_b32_e32 v114, 16, v115
	v_and_b32_e32 v115, 0xffff0000, v115
	v_lshlrev_b32_e32 v148, 16, v116
	v_and_b32_e32 v149, 0xffff0000, v116
	s_nop 1
	v_add_f32_dpp v155, v154, v154 quad_perm:[1,0,3,2] row_mask:0xf bank_mask:0xf
	s_nop 1
	v_add_f32_dpp v154, v155, v155 quad_perm:[2,3,0,1] row_mask:0xf bank_mask:0xf
	s_nop 1
	v_add_f32_dpp v155, v154, v154 row_half_mirror row_mask:0xf bank_mask:0xf
	s_nop 1
	v_add_f32_dpp v154, v155, v155 row_mirror row_mask:0xf bank_mask:0xf
	v_mov_b32_e32 v155, v154
	s_nop 1
	v_permlane16_swap_b32_e32 v154, v155
	s_nop 1
	v_add_f32_e32 v154, v154, v155
	v_mov_b32_e32 v155, v154
	s_nop 1
	v_permlane32_swap_b32_e32 v154, v155
	s_nop 1
	v_add_f32_e32 v154, v154, v155
	v_fmamk_f32 v154, v154, 0x3a000000, v102
	v_mul_f32_e32 v155, 0x4f800000, v154
	v_cmp_gt_f32_e32 vcc, s5, v154
	v_lshlrev_b32_e32 v116, 16, v117
	v_and_b32_e32 v117, 0xffff0000, v117
	v_cndmask_b32_e32 v154, v154, v155, vcc
	v_sqrt_f32_e32 v155, v154
	v_lshlrev_b32_e32 v150, 16, v118
	v_and_b32_e32 v151, 0xffff0000, v118
	v_lshlrev_b32_e32 v118, 16, v119
	v_add_u32_e32 v158, -1, v155
	v_add_u32_e32 v159, 1, v155
	v_fma_f32 v162, -v158, v155, v154
	v_fma_f32 v163, -v159, v155, v154
	v_cmp_ge_f32_e64 s[2:3], 0, v162
	v_and_b32_e32 v119, 0xffff0000, v119
	s_nop 0
	v_cndmask_b32_e64 v155, v155, v158, s[2:3]
	v_cmp_lt_f32_e64 s[2:3], 0, v163
	s_nop 1
	v_cndmask_b32_e64 v155, v155, v159, s[2:3]
	v_mul_f32_e32 v158, 0x37800000, v155
	v_cndmask_b32_e32 v155, v155, v158, vcc
	v_cmp_class_f32_e32 vcc, v154, v103
	s_nop 1
	v_cndmask_b32_e32 v154, v155, v154, vcc
	v_div_scale_f32 v155, s[2:3], v154, v154, 1.0
	v_rcp_f32_e32 v159, v155
	v_div_scale_f32 v158, vcc, 1.0, v154, 1.0
	v_fma_f32 v162, -v155, v159, 1.0
	v_fmac_f32_e32 v159, v162, v159
	v_mul_f32_e32 v162, v158, v159
	v_fma_f32 v163, -v155, v162, v158
	v_fmac_f32_e32 v162, v163, v159
	v_fma_f32 v155, -v155, v162, v158
	v_div_fmas_f32 v155, v155, v159, v162
	v_div_fixup_f32 v154, v155, v154, 1.0
	v_pk_mul_f32 v[152:153], v[154:155], v[152:153] op_sel_hi:[0,1]
	v_pk_mul_f32 v[122:123], v[154:155], v[122:123] op_sel_hi:[0,1]
	v_pk_mul_f32 v[158:159], v[154:155], v[186:187] op_sel_hi:[0,1]
	v_pk_mul_f32 v[124:125], v[154:155], v[124:125] op_sel_hi:[0,1]
	v_pk_mul_f32 v[156:157], v[154:155], v[156:157] op_sel_hi:[0,1]
	v_pk_mul_f32 v[126:127], v[154:155], v[126:127] op_sel_hi:[0,1]
	v_pk_mul_f32 v[160:161], v[160:161], v[154:155] op_sel_hi:[1,0]
	v_pk_mul_f32 v[128:129], v[128:129], v[154:155] op_sel_hi:[1,0]
	v_pk_mul_f32 v[162:163], v[154:155], v[188:189] op_sel_hi:[0,1]
	v_pk_mul_f32 v[130:131], v[154:155], v[130:131] op_sel_hi:[0,1]
	v_pk_mul_f32 v[164:165], v[154:155], v[190:191] op_sel_hi:[0,1]
	v_pk_mul_f32 v[132:133], v[154:155], v[132:133] op_sel_hi:[0,1]
	v_pk_mul_f32 v[166:167], v[154:155], v[166:167] op_sel_hi:[0,1]
	v_pk_mul_f32 v[134:135], v[154:155], v[134:135] op_sel_hi:[0,1]
	v_pk_mul_f32 v[168:169], v[170:171], v[154:155] op_sel_hi:[1,0]
	v_pk_mul_f32 v[120:121], v[120:121], v[154:155] op_sel_hi:[1,0]
	v_pk_fma_f32 v[104:105], v[32:33], v[122:123], v[104:105]
	v_pk_fma_f32 v[122:123], v[34:35], v[152:153], v[136:137]
	v_pk_fma_f32 v[106:107], v[44:45], v[124:125], v[106:107]
	v_pk_fma_f32 v[124:125], v[46:47], v[158:159], v[138:139]
	v_pk_fma_f32 v[108:109], v[36:37], v[126:127], v[108:109]
	v_pk_fma_f32 v[126:127], v[38:39], v[156:157], v[140:141]
	v_pk_fma_f32 v[110:111], v[48:49], v[128:129], v[110:111]
	v_pk_fma_f32 v[128:129], v[50:51], v[160:161], v[142:143]
	v_pk_fma_f32 v[112:113], v[40:41], v[130:131], v[112:113]
	v_pk_fma_f32 v[130:131], v[42:43], v[162:163], v[144:145]
	v_pk_fma_f32 v[114:115], v[52:53], v[132:133], v[114:115]
	v_pk_fma_f32 v[132:133], v[54:55], v[164:165], v[146:147]
	v_pk_fma_f32 v[116:117], v[80:81], v[134:135], v[116:117]
	v_pk_fma_f32 v[134:135], v[82:83], v[166:167], v[148:149]
	v_pk_fma_f32 v[118:119], v[88:89], v[120:121], v[118:119]
	v_pk_fma_f32 v[120:121], v[90:91], v[168:169], v[150:151]
	v_cvt_pk_bf16_f32 v136, v122, v123
	v_cvt_pk_bf16_f32 v137, v104, v105
	v_mov_b32_e32 v154, v123
	v_mov_b32_e32 v155, v125
	v_mov_b32_e32 v158, v105
	v_mov_b32_e32 v159, v107
	v_cvt_pk_bf16_f32 v138, v124, v125
	v_cvt_pk_bf16_f32 v139, v106, v107
	v_cvt_pk_bf16_f32 v140, v126, v127
	v_cvt_pk_bf16_f32 v141, v108, v109
	v_cvt_pk_bf16_f32 v142, v128, v129
	v_cvt_pk_bf16_f32 v143, v110, v111
	v_cvt_pk_bf16_f32 v144, v130, v131
	v_cvt_pk_bf16_f32 v145, v112, v113
	v_cvt_pk_bf16_f32 v146, v132, v133
	v_cvt_pk_bf16_f32 v147, v114, v115
	v_cvt_pk_bf16_f32 v148, v134, v135
	v_cvt_pk_bf16_f32 v149, v116, v117
	v_cvt_pk_bf16_f32 v150, v120, v121
	v_cvt_pk_bf16_f32 v151, v118, v119
	v_mov_b32_e32 v152, v122
	v_mov_b32_e32 v153, v124
	v_mov_b32_e32 v156, v104
	v_mov_b32_e32 v157, v106
	v_pk_mul_f32 v[160:161], v[108:109], v[108:109]
	v_pk_mul_f32 v[162:163], v[126:127], v[126:127]
	global_store_dwordx2 v[98:99], v[136:137], off
	global_store_dwordx2 v[98:99], v[138:139], off offset:512
	global_store_dwordx2 v[98:99], v[140:141], off offset:1024
	global_store_dwordx2 v[98:99], v[142:143], off offset:1536
	global_store_dwordx2 v[98:99], v[144:145], off offset:2048
	global_store_dwordx2 v[98:99], v[146:147], off offset:2560
; __device__ __forceinline__ unsigned pk2(float lo, float hi) { f32x2 v = {lo, hi}; bf16x2_t b = __builtin_convertvector(v, bf16x2_t); return __builtin_bit_cast(unsigned, b); }
; __device__ __forceinline__ float wave_sum(float v) {
; #pragma unroll
;     for (int o = 1; o < 64; o <<= 1) v += __shfl_xor(v, o);
;     return v;
; __device__ __forceinline__ void row_phase(const Params& p, const int li_post, const int li_pre, const int gw, const int ngw, const int lane) {
;     ...
;                 else { u32x2 w; w.x = pk2(v[j][0], v[j][1]); w.y = pk2(v[j][2], v[j][3]); *(u32x2*)((bf16_t*)(p.out + (size_t)row * DM) + col) = w; } }
;         }
;         if (li_pre >= 0) {
;             float ss = 0.f;
; #pragma unroll
;             for (int j = 0; j < 8; ++j) ss += (v[j][0] * v[j][0] + v[j][1] * v[j][1]) + (v[j][2] * v[j][2] + v[j][3] * v[j][3]);
;             ss = wave_sum(ss);
;             const float r = 1.0f / sqrtf(ss * (1.0f / DM) + EPS);
; #pragma unroll
;             for (int j = 0; j < 8; ++j) { const int col = j * 256 + lane * 4;
;                 const f32x4 h = (v[j] * r) * PA[j] + SH[j];
;                 u32x2 w; w.x = pk2(h[0], h[1]); w.y = pk2(h[2], h[3]);
;                 *(u32x2*)(H + (size_t)row * DM + col) = w; }
	global_store_dwordx2 v[98:99], v[148:149], off offset:3072
	global_store_dwordx2 v[98:99], v[150:151], off offset:3584
	v_pk_mul_f32 v[98:99], v[154:155], v[154:155]
	v_pk_mul_f32 v[136:137], v[158:159], v[158:159]
	v_pk_mov_b32 v[138:139], v[162:163], v[160:161] op_sel:[1,0]
	v_mov_b32_e32 v163, v161
	v_pk_fma_f32 v[98:99], v[152:153], v[152:153], v[98:99]
	v_pk_fma_f32 v[136:137], v[156:157], v[156:157], v[136:137]
	v_mul_f32_e32 v164, v128, v128
	v_mul_f32_e32 v166, v110, v110
	v_pk_add_f32 v[138:139], v[138:139], v[162:163]
	v_pk_add_f32 v[98:99], v[98:99], v[136:137]
	v_pk_fma_f32 v[140:141], v[128:129], v[128:129], v[164:165] op_sel_hi:[1,1,0]
	v_pk_fma_f32 v[142:143], v[110:111], v[110:111], v[166:167] op_sel_hi:[1,1,0]
	v_pk_add_f32 v[136:137], v[138:139], v[138:139] op_sel_hi:[0,1]
	v_pk_add_f32 v[98:99], v[98:99], v[98:99] op_sel_hi:[0,1]
	v_pk_mul_f32 v[168:169], v[114:115], v[114:115]
	v_pk_mul_f32 v[170:171], v[132:133], v[132:133]
	v_mul_f32_e32 v140, v130, v130
	v_mul_f32_e32 v142, v131, v131
	v_mul_f32_e32 v136, v112, v112
	v_mul_f32_e32 v98, v113, v113
	v_pk_mov_b32 v[144:145], v[170:171], v[168:169] op_sel:[1,0]
	v_mov_b32_e32 v171, v169
	v_pk_add_f32 v[138:139], v[140:141], v[142:143]
	v_pk_add_f32 v[98:99], v[136:137], v[98:99]
	v_mul_f32_e32 v172, v134, v134
	v_mul_f32_e32 v174, v116, v116
	v_pk_add_f32 v[144:145], v[144:145], v[170:171]
	v_pk_add_f32 v[98:99], v[138:139], v[98:99]
	v_pk_fma_f32 v[146:147], v[134:135], v[134:135], v[172:173] op_sel_hi:[1,1,0]
	v_pk_fma_f32 v[148:149], v[116:117], v[116:117], v[174:175] op_sel_hi:[1,1,0]
	v_pk_add_f32 v[140:141], v[144:145], v[144:145] op_sel_hi:[0,1]
	v_pk_add_f32 v[98:99], v[98:99], v[98:99] op_sel_hi:[0,1]
	v_mul_f32_e32 v146, v120, v120
	v_mul_f32_e32 v148, v121, v121
	v_mul_f32_e32 v140, v118, v118
	v_mul_f32_e32 v98, v119, v119
	v_pk_add_f32 v[142:143], v[146:147], v[148:149]
	v_pk_add_f32 v[98:99], v[140:141], v[98:99]
	s_nop 0
	v_pk_add_f32 v[98:99], v[142:143], v[98:99]
	s_nop 0
	v_add_f32_e32 v98, v98, v99
	s_nop 1
	v_add_f32_dpp v99, v98, v98 quad_perm:[1,0,3,2] row_mask:0xf bank_mask:0xf
	s_nop 1
	v_add_f32_dpp v98, v99, v99 quad_perm:[2,3,0,1] row_mask:0xf bank_mask:0xf
	s_nop 1
	v_add_f32_dpp v99, v98, v98 row_half_mirror row_mask:0xf bank_mask:0xf
	s_nop 1
	v_add_f32_dpp v98, v99, v99 row_mirror row_mask:0xf bank_mask:0xf
	v_mov_b32_e32 v99, v98
	s_nop 1
	v_permlane16_swap_b32_e32 v98, v99
	s_nop 1
	v_add_f32_e32 v98, v98, v99
	v_mov_b32_e32 v99, v98
	s_nop 1
	v_permlane32_swap_b32_e32 v98, v99
	s_nop 1
	v_add_f32_e32 v98, v98, v99
	v_fmamk_f32 v98, v98, 0x3a000000, v102
	v_mul_f32_e32 v99, 0x4f800000, v98
	v_cmp_gt_f32_e32 vcc, s5, v98
	s_nop 1
	v_cndmask_b32_e32 v98, v98, v99, vcc
	v_sqrt_f32_e32 v99, v98
	s_nop 0
	v_add_u32_e32 v136, -1, v99
	v_add_u32_e32 v137, 1, v99
	v_fma_f32 v138, -v136, v99, v98
	v_fma_f32 v139, -v137, v99, v98
	v_cmp_ge_f32_e64 s[2:3], 0, v138
	s_nop 1
	v_cndmask_b32_e64 v99, v99, v136, s[2:3]
	v_cmp_lt_f32_e64 s[2:3], 0, v139
	s_nop 1
	v_cndmask_b32_e64 v99, v99, v137, s[2:3]
	v_mul_f32_e32 v136, 0x37800000, v99
	v_cndmask_b32_e32 v99, v99, v136, vcc
	v_cmp_class_f32_e32 vcc, v98, v103
	s_nop 1
	v_cndmask_b32_e32 v98, v99, v98, vcc
	v_div_scale_f32 v99, s[2:3], v98, v98, 1.0
	v_rcp_f32_e32 v137, v99
	v_div_scale_f32 v136, vcc, 1.0, v98, 1.0
	v_fma_f32 v138, -v99, v137, 1.0
	v_fmac_f32_e32 v137, v138, v137
	v_mul_f32_e32 v138, v136, v137
	v_fma_f32 v139, -v99, v138, v136
	v_fmac_f32_e32 v138, v139, v137
	v_fma_f32 v99, -v99, v138, v136
	v_div_fmas_f32 v99, v99, v137, v138
	v_div_fixup_f32 v98, v99, v98, 1.0
	v_pk_mul_f32 v[122:123], v[122:123], v[98:99] op_sel_hi:[1,0]
	v_pk_mul_f32 v[104:105], v[104:105], v[98:99] op_sel_hi:[1,0]
	v_pk_mul_f32 v[124:125], v[124:125], v[98:99] op_sel_hi:[1,0]
	v_pk_mul_f32 v[106:107], v[106:107], v[98:99] op_sel_hi:[1,0]
	v_pk_mul_f32 v[126:127], v[126:127], v[98:99] op_sel_hi:[1,0]
	v_pk_mul_f32 v[108:109], v[108:109], v[98:99] op_sel_hi:[1,0]
	v_pk_mul_f32 v[128:129], v[128:129], v[98:99] op_sel_hi:[1,0]
	v_pk_mul_f32 v[110:111], v[110:111], v[98:99] op_sel_hi:[1,0]
	v_pk_mul_f32 v[130:131], v[130:131], v[98:99] op_sel_hi:[1,0]
	v_pk_mul_f32 v[112:113], v[112:113], v[98:99] op_sel_hi:[1,0]
	v_pk_mul_f32 v[132:133], v[132:133], v[98:99] op_sel_hi:[1,0]
	v_pk_mul_f32 v[114:115], v[114:115], v[98:99] op_sel_hi:[1,0]
	v_pk_mul_f32 v[134:135], v[134:135], v[98:99] op_sel_hi:[1,0]
	v_pk_mul_f32 v[116:117], v[116:117], v[98:99] op_sel_hi:[1,0]
	v_pk_mul_f32 v[120:121], v[120:121], v[98:99] op_sel_hi:[1,0]
	v_pk_mul_f32 v[98:99], v[118:119], v[98:99] op_sel_hi:[1,0]
	v_pk_fma_f32 v[104:105], v[56:57], v[104:105], v[2:3]
	v_pk_fma_f32 v[118:119], v[58:59], v[122:123], v[0:1]
	v_pk_fma_f32 v[106:107], v[60:61], v[106:107], v[18:19]
	v_pk_fma_f32 v[122:123], v[62:63], v[124:125], v[16:17]
	v_pk_fma_f32 v[108:109], v[64:65], v[108:109], v[6:7]
	v_pk_fma_f32 v[124:125], v[66:67], v[126:127], v[4:5]
	v_pk_fma_f32 v[110:111], v[68:69], v[110:111], v[22:23]
	v_pk_fma_f32 v[126:127], v[70:71], v[128:129], v[20:21]
	v_pk_fma_f32 v[112:113], v[72:73], v[112:113], v[10:11]
	v_pk_fma_f32 v[128:129], v[74:75], v[130:131], v[8:9]
	v_pk_fma_f32 v[114:115], v[76:77], v[114:115], v[26:27]
	v_pk_fma_f32 v[130:131], v[78:79], v[132:133], v[24:25]
	v_pk_fma_f32 v[116:117], v[84:85], v[116:117], v[14:15]
	v_pk_fma_f32 v[132:133], v[86:87], v[134:135], v[12:13]
	v_pk_fma_f32 v[98:99], v[92:93], v[98:99], v[30:31]
	v_pk_fma_f32 v[120:121], v[94:95], v[120:121], v[28:29]
	v_cvt_pk_bf16_f32 v118, v118, v119
	v_cvt_pk_bf16_f32 v119, v104, v105
	v_cvt_pk_bf16_f32 v104, v122, v123
	v_cvt_pk_bf16_f32 v105, v106, v107
	v_cvt_pk_bf16_f32 v106, v124, v125
	v_cvt_pk_bf16_f32 v107, v108, v109
	v_cvt_pk_bf16_f32 v108, v126, v127
	v_cvt_pk_bf16_f32 v109, v110, v111
	v_cvt_pk_bf16_f32 v110, v128, v129
	v_cvt_pk_bf16_f32 v111, v112, v113
	v_cvt_pk_bf16_f32 v112, v130, v131
	v_cvt_pk_bf16_f32 v113, v114, v115
	v_cvt_pk_bf16_f32 v114, v132, v133
	v_cvt_pk_bf16_f32 v115, v116, v117
	v_cvt_pk_bf16_f32 v116, v120, v121
	v_cvt_pk_bf16_f32 v117, v98, v99
	global_store_dwordx2 v[100:101], v[118:119], off
	global_store_dwordx2 v[100:101], v[104:105], off offset:512
	global_store_dwordx2 v[100:101], v[106:107], off offset:1024
	global_store_dwordx2 v[100:101], v[108:109], off offset:1536
	global_store_dwordx2 v[100:101], v[110:111], off offset:2048
	global_store_dwordx2 v[100:101], v[112:113], off offset:2560
	global_store_dwordx2 v[100:101], v[114:115], off offset:3072
	global_store_dwordx2 v[100:101], v[116:117], off offset:3584
	s_cbranch_scc1 .LBB0_757

; __device__ __forceinline__ void pool_window(const bf16_t* __restrict__ U  , bf16_t* __restrict__ A3, const int gtid, const int nthr) {
;     constexpr int LDU = 4096;
;     for (int it = gtid; it < (T / 32) * 256; it += nthr) {
;         const int cg8 = it & 255, tb = it >> 8, c = cg8 * 8, g = c >> 9, w = 2 << g, t0 = tb * 32, s0 = t0 & (SEQ - 1);
;         float sum[8];
; #pragma unroll
;         for (int e = 0; e < 8; ++e) sum[e] = 0.f;
;         if (s0 > 0) {
;             for (int k = 1; k < w; ++k) { const u32x4 uu = *(const u32x4*)(U + (size_t)(t0 - k) * LDU + c);
; __device__ __forceinline__ void phase_pool_window(const Params& p) {
;     ...
;     pool_window((const bf16_t*)(ws + WS_QKVZ), (bf16_t*)(ws + WS_H), bx * NTHREADS + tid, G * NTHREADS);
.LBB0_1329:
	s_or_b64 exec, exec, s[2:3]
	s_waitcnt lgkmcnt(0)
	v_mov_b32_e32 v0, v212
	s_mov_b32 s0, s74
	s_mov_b32 s1, s92
	s_barrier
	s_mov_b32 s2, 0x40000
	v_lshl_add_u32 v22, s1, 9, v0
	v_cmp_gt_i32_e32 vcc, s2, v22
	s_and_saveexec_b64 s[2:3], vcc
	s_cbranch_execz .LBB0_1356
	s_lshl_b32 s18, s0, 9
	s_add_u32 s4, s72, 0x197fe000
	v_lshlrev_b32_e32 v0, 3, v0
	s_movk_i32 s8, 0xe000
	s_addc_u32 s5, s73, 0
	v_lshl_add_u32 v23, s1, 12, v0
	s_lshl_b32 s19, s0, 12
	s_mov_b64 s[6:7], 0
	v_mov_b32_e32 v1, 0
	s_mov_b32 s9, -1
	s_mov_b32 s20, 0x9807000
	s_mov_b64 s[10:11], 0x8000
	s_mov_b64 s[12:13], 0x10000
	s_mov_b64 s[22:23], 0x2000
	s_mov_b32 s21, 0x3ffff
	s_branch .LBB0_1332

; __device__ __forceinline__ void pool_window(const bf16_t* __restrict__ U  , bf16_t* __restrict__ A3, const int gtid, const int nthr) {
;     ...
;         const int cg8 = it & 255, tb = it >> 8, c = cg8 * 8, g = c >> 9, w = 2 << g, t0 = tb * 32, s0 = t0 & (SEQ - 1);
;         float sum[8];
; #pragma unroll
;         for (int e = 0; e < 8; ++e) sum[e] = 0.f;
;         if (s0 > 0) {
;             for (int k = 1; k < w; ++k) { const u32x4 uu = *(const u32x4*)(U + (size_t)(t0 - k) * LDU + c);
;                 sum[0] += bflo(uu.x); sum[1] += bfhi(uu.x); sum[2] += bflo(uu.y); sum[3] += bfhi(uu.y); sum[4] += bflo(uu.z); sum[5] += bfhi(uu.z); sum[6] += bflo(uu.w); sum[7] += bfhi(uu.w); }
.LBB0_1332:
	v_lshlrev_b32_e32 v8, 3, v22
	v_ashrrev_i32_e32 v3, 3, v22
	v_lshlrev_b32_e32 v0, 1, v23
	v_bfe_u32 v2, v8, 9, 2
	v_and_b32_e32 v4, 0xffffffe0, v3
	v_and_b32_e32 v25, 0x1fe0, v3
	v_and_b32_e32 v0, 0xff0, v0
	v_lshlrev_b32_e64 v24, v2, 2
	v_cmp_ne_u32_e32 vcc, 0, v25
	v_ashrrev_i32_e32 v5, 31, v4
	s_and_saveexec_b64 s[0:1], vcc
	s_xor_b64 s[14:15], exec, s[0:1]
	s_cbranch_execz .LBB0_1336
	v_lshlrev_b64 v[6:7], 13, v[4:5]
	v_or_b32_e32 v2, v6, v0
	v_mov_b32_e32 v3, v7
	v_mov_b32_e32 v12, 0
	v_add_u32_e32 v9, -1, v24
	v_lshl_add_u64 v[2:3], s[4:5], 0, v[2:3]
	v_mov_b64_e32 v[42:43], v[2:3]
	global_load_dword v44, v[42:43], off
	v_lshl_add_u64 v[42:43], v[42:43], 0, s[8:9]
	global_load_dword v44, v[42:43], off
	v_lshl_add_u64 v[42:43], v[42:43], 0, s[8:9]
	global_load_dword v44, v[42:43], off
	v_lshl_add_u64 v[42:43], v[42:43], 0, s[8:9]
	global_load_dword v44, v[42:43], off
	v_lshl_add_u64 v[42:43], v[42:43], 0, s[8:9]
	global_load_dword v44, v[42:43], off
	v_lshl_add_u64 v[42:43], v[42:43], 0, s[8:9]
	global_load_dword v44, v[42:43], off
	v_lshl_add_u64 v[42:43], v[42:43], 0, s[8:9]
	global_load_dword v44, v[42:43], off
	v_lshl_add_u64 v[42:43], v[42:43], 0, s[8:9]
	global_load_dword v44, v[42:43], off
	v_lshl_add_u64 v[42:43], v[42:43], 0, s[8:9]
	global_load_dword v44, v[42:43], off
	v_lshl_add_u64 v[42:43], v[42:43], 0, s[8:9]
	global_load_dword v44, v[42:43], off
	v_lshl_add_u64 v[42:43], v[42:43], 0, s[8:9]
	global_load_dword v44, v[42:43], off
	v_lshl_add_u64 v[42:43], v[42:43], 0, s[8:9]
	global_load_dword v44, v[42:43], off
	v_lshl_add_u64 v[42:43], v[42:43], 0, s[8:9]
	global_load_dword v44, v[42:43], off
	v_lshl_add_u64 v[42:43], v[42:43], 0, s[8:9]
	global_load_dword v44, v[42:43], off
	v_lshl_add_u64 v[42:43], v[42:43], 0, s[8:9]
	global_load_dword v44, v[42:43], off
	v_lshl_add_u64 v[42:43], v[2:3], 0, s[22:23]
	global_load_dword v44, v[42:43], off
	v_lshl_add_u64 v[42:43], v[42:43], 0, s[22:23]
	global_load_dword v44, v[42:43], off
	v_lshl_add_u64 v[42:43], v[42:43], 0, s[22:23]
	global_load_dword v44, v[42:43], off
	v_lshl_add_u64 v[42:43], v[42:43], 0, s[22:23]
	global_load_dword v44, v[42:43], off
	v_lshl_add_u64 v[42:43], v[42:43], 0, s[22:23]
	global_load_dword v44, v[42:43], off
	v_lshl_add_u64 v[42:43], v[42:43], 0, s[22:23]
	global_load_dword v44, v[42:43], off
	v_lshl_add_u64 v[42:43], v[42:43], 0, s[22:23]
	global_load_dword v44, v[42:43], off
	v_lshl_add_u64 v[42:43], v[42:43], 0, s[22:23]
	global_load_dword v44, v[42:43], off
	s_mov_b64 s[16:17], 0
	v_mov_b32_e32 v13, v12
	v_mov_b32_e32 v14, v12
	v_mov_b32_e32 v15, v12
	v_mov_b32_e32 v16, v12
	v_mov_b32_e32 v17, v12
	v_mov_b32_e32 v18, v12
	v_mov_b32_e32 v19, v12

; __device__ __forceinline__ unsigned pk2(float lo, float hi) { f32x2 v = {lo, hi}; bf16x2_t b = __builtin_convertvector(v, bf16x2_t); return __builtin_bit_cast(unsigned, b); }
; __device__ __forceinline__ void pool_window(const bf16_t* __restrict__ U  , bf16_t* __restrict__ A3, const int gtid, const int nthr) {
;     ...
;         for (int i = 0; i < 32; ++i) {
;             const int t = t0 + i, s = s0 + i;
;             const u32x4 uu = *(const u32x4*)(U + (size_t)t * LDU + c);
;             float cu[8] = {bflo(uu.x), bfhi(uu.x), bflo(uu.y), bfhi(uu.y), bflo(uu.z), bfhi(uu.z), bflo(uu.w), bfhi(uu.w)};
;             const float rc = 1.0f / (float)((s + 1) < w ? (s + 1) : w);
;             float o[8];
; #pragma unroll
;             for (int e = 0; e < 8; ++e) { sum[e] += cu[e]; o[e] = sum[e] * rc - cu[e]; }
;             u32x4 ww; ww.x = pk2(o[0], o[1]); ww.y = pk2(o[2], o[3]); ww.z = pk2(o[4], o[5]); ww.w = pk2(o[6], o[7]);
;             *(u32x4*)(A3 + (size_t)t * DM + c) = ww;
;             if (s + 1 >= w) { const u32x4 ud = *(const u32x4*)(U + (size_t)(t - w + 1) * LDU + c);
;                 sum[0] -= bflo(ud.x); sum[1] -= bfhi(ud.x); sum[2] -= bflo(ud.y); sum[3] -= bfhi(ud.y); sum[4] -= bflo(ud.z); sum[5] -= bfhi(ud.z); sum[6] -= bflo(ud.w); sum[7] -= bfhi(ud.w); }
.LBB0_1340:
	v_lshl_add_u64 v[8:9], v[6:7], 0, v[0:1]
	v_add_co_u32_e32 v10, vcc, 0x19800000, v8
	v_add_u32_e32 v27, s16, v25
	s_nop 0
	v_addc_co_u32_e32 v11, vcc, 0, v9, vcc
	global_load_dwordx4 v[28:31], v[10:11], off
	v_lshl_add_u64 v[42:43], v[10:11], 0, s[12:13]
	global_load_dword v44, v[42:43], off
	v_lshl_add_u64 v[42:43], v[42:43], 0, s[22:23]
	global_load_dword v44, v[42:43], off
	v_lshl_add_u64 v[42:43], v[42:43], 0, s[22:23]
	global_load_dword v44, v[42:43], off
	v_lshl_add_u64 v[42:43], v[42:43], 0, s[22:23]
	global_load_dword v44, v[42:43], off
	v_lshl_add_u64 v[42:43], v[42:43], 0, s[22:23]
	global_load_dword v44, v[42:43], off
	v_lshl_add_u64 v[42:43], v[42:43], 0, s[22:23]
	global_load_dword v44, v[42:43], off
	v_lshl_add_u64 v[42:43], v[42:43], 0, s[22:23]
	global_load_dword v44, v[42:43], off
	v_lshl_add_u64 v[42:43], v[42:43], 0, s[22:23]
	global_load_dword v44, v[42:43], off
	v_add_u32_e32 v40, 1, v27
	v_min_u32_e32 v10, v40, v24
	v_cvt_f32_ubyte0_e32 v20, v10
	v_div_scale_f32 v21, s[0:1], v20, v20, 1.0
	v_rcp_f32_e32 v32, v21
	v_div_scale_f32 v33, vcc, 1.0, v20, 1.0
	v_lshl_add_u64 v[10:11], v[4:5], 0, v[0:1]
	v_fma_f32 v34, -v21, v32, 1.0
	v_fmac_f32_e32 v32, v34, v32
	v_mul_f32_e32 v34, v33, v32
	v_fma_f32 v35, -v21, v34, v33
	v_fmac_f32_e32 v34, v35, v32
	v_fma_f32 v21, -v21, v34, v33
	v_div_fmas_f32 v21, v21, v32, v34
	v_add_co_u32_e32 v32, vcc, 0x9800000, v10
	v_div_fixup_f32 v34, v21, v20, 1.0
	s_nop 0
	v_addc_co_u32_e32 v33, vcc, 0, v11, vcc
	v_cmp_ge_u32_e32 vcc, v40, v24
	s_waitcnt vmcnt(0)
	v_lshlrev_b32_e32 v36, 16, v28
	v_and_b32_e32 v37, 0xffff0000, v28
	v_lshlrev_b32_e32 v28, 16, v29
	v_and_b32_e32 v29, 0xffff0000, v29
	v_lshlrev_b32_e32 v38, 16, v30
	v_and_b32_e32 v39, 0xffff0000, v30
	v_lshlrev_b32_e32 v30, 16, v31
	v_and_b32_e32 v31, 0xffff0000, v31
	v_pk_add_f32 v[14:15], v[14:15], v[36:37]
	v_pk_add_f32 v[16:17], v[16:17], v[28:29]
	v_pk_add_f32 v[18:19], v[18:19], v[38:39]
	v_pk_add_f32 v[20:21], v[12:13], v[30:31]
	v_pk_fma_f32 v[12:13], v[34:35], v[14:15], v[36:37] op_sel_hi:[0,1,1] neg_lo:[0,0,1] neg_hi:[0,0,1]
	v_pk_fma_f32 v[36:37], v[34:35], v[16:17], v[28:29] op_sel_hi:[0,1,1] neg_lo:[0,0,1] neg_hi:[0,0,1]
	v_pk_fma_f32 v[38:39], v[34:35], v[18:19], v[38:39] op_sel_hi:[0,1,1] neg_lo:[0,0,1] neg_hi:[0,0,1]
	v_pk_fma_f32 v[34:35], v[34:35], v[20:21], v[30:31] op_sel_hi:[0,1,1] neg_lo:[0,0,1] neg_hi:[0,0,1]
	v_cvt_pk_bf16_f32 v28, v12, v13
	v_cvt_pk_bf16_f32 v29, v36, v37
	v_cvt_pk_bf16_f32 v30, v38, v39
	v_cvt_pk_bf16_f32 v31, v34, v35
	global_store_dwordx4 v[32:33], v[28:31], off
	s_and_saveexec_b64 s[14:15], vcc
	s_cbranch_execz .LBB0_1342
	v_add3_u32 v12, v26, s16, 1
	v_ashrrev_i32_e32 v13, 31, v12
	v_lshlrev_b64 v[12:13], 13, v[12:13]
	v_lshl_add_u64 v[12:13], v[2:3], 0, v[12:13]
	global_load_dwordx4 v[28:31], v[12:13], off
	s_waitcnt vmcnt(0)
	v_lshlrev_b32_e32 v12, 16, v28
	v_and_b32_e32 v13, 0xffff0000, v28
	v_lshlrev_b32_e32 v28, 16, v29
	v_and_b32_e32 v29, 0xffff0000, v29
	v_lshlrev_b32_e32 v32, 16, v30
	v_and_b32_e32 v33, 0xffff0000, v30
	v_lshlrev_b32_e32 v30, 16, v31
	v_and_b32_e32 v31, 0xffff0000, v31
	v_pk_add_f32 v[14:15], v[14:15], v[12:13] neg_lo:[0,1] neg_hi:[0,1]
	v_pk_add_f32 v[16:17], v[16:17], v[28:29] neg_lo:[0,1] neg_hi:[0,1]
	v_pk_add_f32 v[18:19], v[18:19], v[32:33] neg_lo:[0,1] neg_hi:[0,1]
	v_pk_add_f32 v[20:21], v[20:21], v[30:31] neg_lo:[0,1] neg_hi:[0,1]

; __device__ __forceinline__ void row_phase(const Params& p, const int li_post, const int li_pre, const int gw, const int ngw, const int lane) {
;     ...
;     for (int i = i0; i < SEQ; i += istep) {
;         const int row = b * SEQ + i;
;         f32x4 v[8];
; #pragma unroll
;         for (int j = 0; j < 8; ++j) {
;             if (li_post <= 0) v[j] = *(const f32x4*)(p.x + (size_t)row * DM + j * 256 + lane * 4);
;             else { const u32x2 xx = *(const u32x2*)((const bf16_t*)(p.out + (size_t)row * DM) + j * 256 + lane * 4); v[j] = (f32x4){bflo(xx.x), bfhi(xx.x), bflo(xx.y), bfhi(xx.y)}; }
;         }
;         if (li_post >= 0) {
;             f32x4 y[8]; float ss = 0.f;
; #pragma unroll
;             for (int j = 0; j < 8; ++j) { const u32x2 yy = *(const u32x2*)(Y + (size_t)row * DM + j * 256 + lane * 4); y[j] = (f32x4){bflo(yy.x), bfhi(yy.x), bflo(yy.y), bfhi(yy.y)}; ss += (y[j][0] * y[j][0] + y[j][1] * y[j][1]) + (y[j][2] * y[j][2] + y[j][3] * y[j][3]); }
.LBB0_1568:
	v_lshl_add_u64 v[36:37], s[8:9], 0, v[0:1]
	v_lshl_add_u64 v[40:41], s[4:5], 0, v[0:1]
	global_load_dwordx2 v[44:45], v[36:37], off
	global_load_dwordx2 v[46:47], v[36:37], off offset:512
	global_load_dwordx2 v[48:49], v[36:37], off offset:1024
	global_load_dwordx2 v[50:51], v[36:37], off offset:1536
	global_load_dwordx2 v[52:53], v[36:37], off offset:2048
	global_load_dwordx2 v[54:55], v[36:37], off offset:2560
	global_load_dwordx2 v[56:57], v[36:37], off offset:3072
	global_load_dwordx2 v[58:59], v[36:37], off offset:3584
	v_add_co_u32_e32 v36, vcc, s14, v40
	v_lshl_add_u64 v[38:39], s[8:9], 0, v[2:3]
	s_nop 0
	v_addc_co_u32_e32 v37, vcc, 0, v41, vcc
	global_load_dwordx2 v[60:61], v[36:37], off
	global_load_dwordx2 v[62:63], v[36:37], off offset:512
	global_load_dwordx2 v[64:65], v[36:37], off offset:1024
	global_load_dwordx2 v[66:67], v[36:37], off offset:1536
	global_load_dwordx2 v[68:69], v[36:37], off offset:2048
	global_load_dwordx2 v[70:71], v[36:37], off offset:2560
	global_load_dwordx2 v[72:73], v[36:37], off offset:3072
	global_load_dwordx2 v[74:75], v[36:37], off offset:3584
	v_add_co_u32_e32 v40, vcc, s13, v38
	s_add_i32 s12, s12, s2
	s_nop 0
	v_addc_co_u32_e32 v41, vcc, 0, v39, vcc
	s_add_u32 s4, s4, s6
	s_addc_u32 s5, s5, s7
	s_add_u32 s8, s8, s10
	s_addc_u32 s9, s9, s11
	s_cmpk_lt_i32 s12, 0x2000
	s_waitcnt vmcnt(15)
	v_lshlrev_b32_e32 v36, 16, v44
	s_waitcnt vmcnt(14)
	v_lshlrev_b32_e32 v78, 16, v47
	v_and_b32_e32 v79, 0xffff0000, v47
	s_waitcnt vmcnt(13)
	v_lshlrev_b32_e32 v82, 16, v49
	v_and_b32_e32 v83, 0xffff0000, v49
	s_waitcnt vmcnt(11)
	v_lshlrev_b32_e32 v88, 16, v52
	v_and_b32_e32 v89, 0xffff0000, v52
	v_lshlrev_b32_e32 v90, 16, v53
	v_and_b32_e32 v91, 0xffff0000, v53
	s_waitcnt vmcnt(7)
	v_and_b32_e32 v47, 0xffff0000, v60
	v_and_b32_e32 v49, 0xffff0000, v61
	s_waitcnt vmcnt(6)
	v_and_b32_e32 v53, 0xffff0000, v63
	v_and_b32_e32 v52, 0xffff0000, v62
	v_lshlrev_b32_e32 v76, 16, v46
	v_and_b32_e32 v77, 0xffff0000, v46
	v_lshlrev_b32_e32 v80, 16, v48
	v_and_b32_e32 v81, 0xffff0000, v48
	v_lshlrev_b32_e32 v84, 16, v50
	v_and_b32_e32 v85, 0xffff0000, v50
	v_lshlrev_b32_e32 v86, 16, v51
	v_and_b32_e32 v87, 0xffff0000, v51
	v_lshlrev_b32_e32 v94, 16, v55
	v_and_b32_e32 v95, 0xffff0000, v55
	v_lshlrev_b32_e32 v100, 16, v58
	v_and_b32_e32 v101, 0xffff0000, v58
	v_lshlrev_b32_e32 v102, 16, v59
	v_and_b32_e32 v103, 0xffff0000, v59
	v_lshlrev_b32_e32 v46, 16, v60
	v_lshlrev_b32_e32 v48, 16, v61
	v_lshlrev_b32_e32 v51, 16, v63
	v_lshlrev_b32_e32 v50, 16, v62
	s_waitcnt vmcnt(5)
	v_and_b32_e32 v55, 0xffff0000, v64
	s_waitcnt vmcnt(4)
	v_lshlrev_b32_e32 v59, 16, v66
	s_waitcnt vmcnt(0)
	v_lshlrev_b32_e32 v107, 16, v74
	v_mul_f32_e32 v58, v49, v49
	v_pk_mul_f32 v[110:111], v[52:53], v[52:53]
	v_mul_f32_e32 v106, v47, v47
	v_lshlrev_b32_e32 v92, 16, v54
	v_and_b32_e32 v93, 0xffff0000, v54
	v_lshlrev_b32_e32 v98, 16, v57
	v_and_b32_e32 v99, 0xffff0000, v57
	v_lshlrev_b32_e32 v54, 16, v64
	v_and_b32_e32 v57, 0xffff0000, v65
	v_mov_b32_e32 v113, v59
	v_mul_f32_e32 v112, v55, v55
	v_mov_b32_e32 v124, v50
	v_mov_b32_e32 v125, v52
	v_mov_b32_e32 v52, v51
	v_pk_fma_f32 v[130:131], v[48:49], v[48:49], v[58:59] op_sel_hi:[1,1,0]
	v_pk_fma_f32 v[50:51], v[50:51], v[50:51], v[110:111]
	v_pk_fma_f32 v[110:111], v[46:47], v[46:47], v[106:107] op_sel_hi:[1,1,0]
	v_lshlrev_b32_e32 v96, 16, v56
	v_and_b32_e32 v97, 0xffff0000, v56
	v_lshlrev_b32_e32 v56, 16, v65
	v_and_b32_e32 v61, 0xffff0000, v66
	v_lshlrev_b32_e32 v62, 16, v67
	v_and_b32_e32 v63, 0xffff0000, v67
	v_mul_f32_e32 v114, v57, v57
	v_mov_b32_e32 v115, v107
	v_pk_fma_f32 v[132:133], v[54:55], v[54:55], v[112:113] op_sel_hi:[1,1,0]
	v_mov_b32_e32 v58, v110
	v_mov_b32_e32 v112, v130
	v_mul_f32_e32 v121, v61, v61
	v_mul_f32_e32 v123, v62, v62
	v_mul_f32_e32 v136, v63, v63
	v_mov_b32_e32 v60, v59
	v_pk_fma_f32 v[134:135], v[56:57], v[56:57], v[114:115] op_sel_hi:[1,1,0]
	v_pk_add_f32 v[110:111], v[110:111], v[130:131]
	v_pk_add_f32 v[50:51], v[50:51], v[50:51] op_sel:[0,1] op_sel_hi:[1,0]
	v_pk_mul_f32 v[58:59], v[58:59], v[112:113]
	v_and_b32_e32 v67, 0xffff0000, v69
	v_and_b32_e32 v66, 0xffff0000, v68
	v_mov_b32_e32 v133, v123
	v_mov_b32_e32 v135, v136
	v_mov_b32_e32 v51, v121
	v_mov_b32_e32 v111, v59
	v_lshlrev_b32_e32 v65, 16, v69
	v_lshlrev_b32_e32 v64, 16, v68
	v_pk_mul_f32 v[116:117], v[66:67], v[66:67]
	v_pk_add_f32 v[112:113], v[132:133], v[134:135]
	v_pk_add_f32 v[50:51], v[110:111], v[50:51]
	v_lshlrev_b32_e32 v69, 16, v71
	v_lshlrev_b32_e32 v68, 16, v70
	v_and_b32_e32 v71, 0xffff0000, v71
	v_and_b32_e32 v70, 0xffff0000, v70
	v_mov_b32_e32 v126, v64
	v_mov_b32_e32 v127, v66
	v_mov_b32_e32 v66, v65
	v_pk_fma_f32 v[64:65], v[64:65], v[64:65], v[116:117]
	v_pk_add_f32 v[50:51], v[50:51], v[112:113]
	v_lshlrev_b32_e32 v104, 16, v72
	v_and_b32_e32 v105, 0xffff0000, v72
	v_lshlrev_b32_e32 v72, 16, v73
	v_and_b32_e32 v73, 0xffff0000, v73
	v_pk_mul_f32 v[118:119], v[70:71], v[70:71]
	v_pk_add_f32 v[64:65], v[64:65], v[64:65] op_sel:[0,1] op_sel_hi:[1,0]
; __device__ __forceinline__ unsigned pk2(float lo, float hi) { f32x2 v = {lo, hi}; bf16x2_t b = __builtin_convertvector(v, bf16x2_t); return __builtin_bit_cast(unsigned, b); }
; __device__ __forceinline__ float wave_sum(float v) {
; #pragma unroll
;     for (int o = 1; o < 64; o <<= 1) v += __shfl_xor(v, o);
;     return v;
; __device__ __forceinline__ void row_phase(const Params& p, const int li_post, const int li_pre, const int gw, const int ngw, const int lane) {
;     ...
;             for (int j = 0; j < 8; ++j) { const u32x2 yy = *(const u32x2*)(Y + (size_t)row * DM + j * 256 + lane * 4); y[j] = (f32x4){bflo(yy.x), bfhi(yy.x), bflo(yy.y), bfhi(yy.y)}; ss += (y[j][0] * y[j][0] + y[j][1] * y[j][1]) + (y[j][2] * y[j][2] + y[j][3] * y[j][3]); }
;             ss = wave_sum(ss);
;             const float r = 1.0f / sqrtf(ss * (1.0f / DM) + EPS);
; #pragma unroll
;             for (int j = 0; j < 8; ++j) { const int col = j * 256 + lane * 4;
;                 v[j] = v[j] + (y[j] * r) * GP[j];
;                 if (li_post == 3) *(f32x4*)(p.out + (size_t)row * DM + col) = v[j];
;                 else { u32x2 w; w.x = pk2(v[j][0], v[j][1]); w.y = pk2(v[j][2], v[j][3]); *(u32x2*)((bf16_t*)(p.out + (size_t)row * DM) + col) = w; } }
	v_pk_add_f32 v[50:51], v[50:51], v[50:51] op_sel:[0,1] op_sel_hi:[1,0]
	v_and_b32_e32 v109, 0xffff0000, v74
	v_lshlrev_b32_e32 v74, 16, v75
	v_and_b32_e32 v75, 0xffff0000, v75
	v_mul_f32_e32 v120, v105, v105
	v_mul_f32_e32 v122, v73, v73
	v_mov_b32_e32 v128, v68
	v_mov_b32_e32 v129, v70
	v_mov_b32_e32 v70, v69
	v_pk_fma_f32 v[68:69], v[68:69], v[68:69], v[118:119]
	v_mov_b32_e32 v114, v64
	v_mov_b32_e32 v106, v50
	v_mul_f32_e32 v137, v109, v109
	v_mul_f32_e32 v138, v74, v74
	v_mul_f32_e32 v139, v75, v75
	v_pk_fma_f32 v[116:117], v[104:105], v[104:105], v[120:121] op_sel_hi:[1,1,0]
	v_pk_fma_f32 v[118:119], v[72:73], v[72:73], v[122:123] op_sel_hi:[1,1,0]
	v_pk_add_f32 v[68:69], v[68:69], v[68:69] op_sel:[0,1] op_sel_hi:[1,0]
	v_pk_add_f32 v[50:51], v[50:51], v[64:65]
	v_pk_mul_f32 v[58:59], v[106:107], v[114:115]
	v_mov_b32_e32 v117, v138
	v_mov_b32_e32 v119, v139
	v_mov_b32_e32 v69, v137
	v_mov_b32_e32 v51, v59
	v_pk_add_f32 v[116:117], v[116:117], v[118:119]
	v_pk_add_f32 v[50:51], v[50:51], v[68:69]
	v_and_b32_e32 v37, 0xffff0000, v44
	v_pk_add_f32 v[50:51], v[50:51], v[116:117]
	v_lshlrev_b32_e32 v44, 16, v45
	v_add_f32_e32 v50, v50, v51
	v_and_b32_e32 v45, 0xffff0000, v45
	v_mov_b32_e32 v108, v107
	s_nop 1
	v_add_f32_dpp v51, v50, v50 quad_perm:[1,0,3,2] row_mask:0xf bank_mask:0xf
	s_nop 1
	v_add_f32_dpp v50, v51, v51 quad_perm:[2,3,0,1] row_mask:0xf bank_mask:0xf
	s_nop 1
	v_add_f32_dpp v51, v50, v50 row_half_mirror row_mask:0xf bank_mask:0xf
	s_nop 1
	v_add_f32_dpp v50, v51, v51 row_mirror row_mask:0xf bank_mask:0xf
	v_mov_b32_e32 v51, v50
	s_nop 1
	v_permlane16_swap_b32_e32 v50, v51
	s_nop 1
	v_add_f32_e32 v50, v50, v51
	v_mov_b32_e32 v51, v50
	s_nop 1
	v_permlane32_swap_b32_e32 v50, v51
	s_nop 1
	v_add_f32_e32 v50, v50, v51
	v_fmamk_f32 v50, v50, 0x3a000000, v42
	v_mul_f32_e32 v51, 0x4f800000, v50
	v_cmp_gt_f32_e32 vcc, s15, v50
	s_nop 1
	v_cndmask_b32_e32 v50, v50, v51, vcc
	v_sqrt_f32_e32 v51, v50
	s_nop 0
	v_add_u32_e32 v58, -1, v51
	v_add_u32_e32 v59, 1, v51
	v_fma_f32 v64, -v58, v51, v50
	v_fma_f32 v65, -v59, v51, v50
	v_cmp_ge_f32_e64 s[0:1], 0, v64
	s_nop 1
	v_cndmask_b32_e64 v51, v51, v58, s[0:1]
	v_cmp_lt_f32_e64 s[0:1], 0, v65
	s_nop 1
	v_cndmask_b32_e64 v51, v51, v59, s[0:1]
	v_mul_f32_e32 v58, 0x37800000, v51
	v_cndmask_b32_e32 v51, v51, v58, vcc
	v_cmp_class_f32_e32 vcc, v50, v43
	s_nop 1
	v_cndmask_b32_e32 v50, v51, v50, vcc
	v_div_scale_f32 v51, s[0:1], v50, v50, 1.0
	v_rcp_f32_e32 v59, v51
	v_div_scale_f32 v58, vcc, 1.0, v50, 1.0
	v_fma_f32 v64, -v51, v59, 1.0
	v_fmac_f32_e32 v59, v64, v59
	v_mul_f32_e32 v64, v58, v59
	v_fma_f32 v65, -v51, v64, v58
	v_fmac_f32_e32 v64, v65, v59
	v_fma_f32 v51, -v51, v64, v58
	v_div_fmas_f32 v51, v51, v59, v64
	v_div_fixup_f32 v50, v51, v50, 1.0
	v_pk_mul_f32 v[58:59], v[50:51], v[46:47] op_sel_hi:[0,1]
	v_pk_mul_f32 v[46:47], v[50:51], v[48:49] op_sel_hi:[0,1]
	v_pk_mul_f32 v[48:49], v[50:51], v[124:125] op_sel_hi:[0,1]
	v_pk_mul_f32 v[52:53], v[50:51], v[52:53] op_sel_hi:[0,1]
	v_pk_mul_f32 v[64:65], v[50:51], v[54:55] op_sel_hi:[0,1]
	v_pk_mul_f32 v[54:55], v[50:51], v[56:57] op_sel_hi:[0,1]
	v_pk_mul_f32 v[56:57], v[60:61], v[50:51] op_sel_hi:[1,0]
	v_pk_mul_f32 v[60:61], v[62:63], v[50:51] op_sel_hi:[1,0]
	v_pk_mul_f32 v[68:69], v[50:51], v[126:127] op_sel_hi:[0,1]
	v_pk_mul_f32 v[62:63], v[50:51], v[66:67] op_sel_hi:[0,1]
	v_pk_mul_f32 v[106:107], v[50:51], v[128:129] op_sel_hi:[0,1]
	v_pk_mul_f32 v[66:67], v[50:51], v[70:71] op_sel_hi:[0,1]
	v_pk_mul_f32 v[104:105], v[50:51], v[104:105] op_sel_hi:[0,1]
	v_pk_mul_f32 v[70:71], v[50:51], v[72:73] op_sel_hi:[0,1]
	v_pk_mul_f32 v[72:73], v[108:109], v[50:51] op_sel_hi:[1,0]
	v_pk_mul_f32 v[74:75], v[74:75], v[50:51] op_sel_hi:[1,0]
	v_pk_fma_f32 v[46:47], v[4:5], v[46:47], v[44:45]
	v_pk_fma_f32 v[44:45], v[6:7], v[58:59], v[36:37]
	v_pk_fma_f32 v[50:51], v[8:9], v[52:53], v[78:79]
	v_pk_fma_f32 v[48:49], v[10:11], v[48:49], v[76:77]
	v_pk_fma_f32 v[54:55], v[12:13], v[54:55], v[82:83]
	v_pk_fma_f32 v[52:53], v[14:15], v[64:65], v[80:81]
	v_pk_fma_f32 v[58:59], v[16:17], v[60:61], v[86:87]
	v_pk_fma_f32 v[56:57], v[18:19], v[56:57], v[84:85]
	v_pk_fma_f32 v[62:63], v[20:21], v[62:63], v[90:91]
	v_pk_fma_f32 v[60:61], v[22:23], v[68:69], v[88:89]
	v_pk_fma_f32 v[66:67], v[24:25], v[66:67], v[94:95]
	v_pk_fma_f32 v[64:65], v[26:27], v[106:107], v[92:93]
	v_pk_fma_f32 v[70:71], v[28:29], v[70:71], v[98:99]
	v_pk_fma_f32 v[68:69], v[30:31], v[104:105], v[96:97]
	v_pk_fma_f32 v[74:75], v[32:33], v[74:75], v[102:103]
	v_pk_fma_f32 v[72:73], v[34:35], v[72:73], v[100:101]
	global_store_dwordx4 v[38:39], v[44:47], off
	global_store_dwordx4 v[38:39], v[48:51], off offset:1024
	global_store_dwordx4 v[38:39], v[52:55], off offset:2048
	global_store_dwordx4 v[38:39], v[56:59], off offset:3072
	global_store_dwordx4 v[40:41], v[60:63], off
	global_store_dwordx4 v[40:41], v[64:67], off offset:1024
	global_store_dwordx4 v[40:41], v[68:71], off offset:2048
	global_store_dwordx4 v[40:41], v[72:75], off offset:3072
	s_cbranch_scc1 .LBB0_1568
